# v26 + 256-byte alignment of the six GEMM k-loop latches and four attention loop heads
# speedup vs baseline: 1.0092x; 1.0092x over previous
.LBB0_107:
	s_load_dwordx4 s[40:43], s[0:1], 0xe8
	v_mov_b32_e32 v201, v206
	s_lshl_b32 s62, s44, 8
	s_load_dwordx2 s[64:65], s[20:21], 0x0
	s_mul_i32 s49, s45, 0x1600
	s_mul_hi_i32 s48, s45, 0x1600
	v_ashrrev_i32_e32 v40, 3, v201
	s_waitcnt lgkmcnt(0)
	s_add_u32 s20, s42, s49
	v_lshlrev_b32_e32 v0, 4, v201
	v_mul_lo_u32 v2, v40, s93
	s_movk_i32 s5, 0x70
	s_addc_u32 s21, s43, s48
	s_ashr_i32 s63, s62, 31
	s_mul_i32 s61, s44, 0x160000
	v_and_or_b32 v0, v0, s5, v2
	s_mul_hi_i32 s72, s62, 0x1600
	s_add_u32 s40, s50, s61
	v_add_u32_e32 v34, 0x58000, v0
	v_add_u32_e32 v36, 0xb0000, v0
	s_addc_u32 s41, s51, s72
	global_load_dwordx4 v[2:5], v0, s[20:21]
	global_load_dwordx4 v[6:9], v0, s[40:41]
	global_load_dwordx4 v[10:13], v34, s[20:21]
	global_load_dwordx4 v[14:17], v34, s[40:41]
	global_load_dwordx4 v[18:21], v36, s[20:21]
	global_load_dwordx4 v[22:25], v36, s[40:41]
	v_add_u32_e32 v38, 0x108000, v0
	global_load_dwordx4 v[26:29], v38, s[20:21]
	global_load_dwordx4 v[30:33], v38, s[40:41]
	global_load_dwordx4 v[144:147], v0, s[20:21] offset:128
	global_load_dwordx4 v[148:151], v0, s[40:41] offset:128
	global_load_dwordx4 v[152:155], v34, s[20:21] offset:128
	global_load_dwordx4 v[156:159], v34, s[40:41] offset:128
	global_load_dwordx4 v[160:163], v36, s[20:21] offset:128
	global_load_dwordx4 v[164:167], v36, s[40:41] offset:128
	global_load_dwordx4 v[168:171], v38, s[20:21] offset:128
	global_load_dwordx4 v[172:175], v38, s[40:41] offset:128
	v_lshlrev_b32_e32 v48, 7, v40
	v_lshrrev_b32_e32 v40, 1, v40
	s_movk_i32 s4, 0x100
	v_xor_b32_e32 v40, v40, v201
	s_add_u32 s20, s89, s61
	v_mov_b32_e32 v35, v1
	v_mov_b32_e32 v37, v1
	v_mov_b32_e32 v39, v1
	v_cmp_gt_u32_e64 s[44:45], s4, v201
	v_lshlrev_b32_e32 v40, 4, v40
	s_addc_u32 s21, s90, s72
	v_readlane_b32 s4, v254, 35
	v_lshlrev_b32_e32 v42, 7, v201
	v_bfe_u32 v43, v201, 1, 3
	v_lshrrev_b32_e32 v229, 5, v201
	v_bfe_u32 v204, v201, 5, 1
	v_and_or_b32 v198, v40, s5, v48
	v_lshl_add_u64 v[176:177], s[20:21], 0, v[38:39]
	v_lshl_add_u64 v[178:179], s[20:21], 0, v[36:37]
	v_lshl_add_u64 v[180:181], s[20:21], 0, v[34:35]
	v_lshl_add_u64 v[182:183], s[20:21], 0, v[0:1]
	s_add_u32 s20, s4, s49
	v_readlane_b32 s4, v254, 36
	v_ashrrev_i32_e32 v41, 8, v201
	v_and_b32_e32 v44, 0xf80, v42
	v_and_b32_e32 v42, 0x6f80, v42
	v_bitop3_b32 v45, v229, v43, 1 bitop3:0x6c
	v_bitop3_b32 v46, v204, v43, 2 bitop3:0x36
	v_bitop3_b32 v47, v204, v43, 4 bitop3:0x36
	v_bitop3_b32 v43, v204, v43, 6 bitop3:0x36
	s_addc_u32 s21, s4, s48
	v_cmp_eq_u32_e64 s[42:43], 1, v41
	v_cmp_ne_u32_e64 s[46:47], 1, v41
	v_lshl_or_b32 v192, v41, 14, v44
	v_or_b32_e32 v193, 0x8000, v42
	v_lshlrev_b32_e32 v194, 4, v45
	v_lshlrev_b32_e32 v195, 4, v46
	v_lshlrev_b32_e32 v196, 4, v47
	v_lshlrev_b32_e32 v197, 4, v43
	v_lshl_add_u64 v[184:185], s[20:21], 0, v[38:39]
	v_lshl_add_u64 v[186:187], s[20:21], 0, v[36:37]
	v_lshl_add_u64 v[188:189], s[20:21], 0, v[34:35]
	v_lshl_add_u64 v[190:191], s[20:21], 0, v[0:1]
	v_mov_b32_e32 v0, v1
	v_cmp_lt_u32_e32 vcc, s76, v201
	s_mov_b64 s[20:21], 0
	s_mov_b32 s61, 0
	s_mov_b32 s72, 0
	s_waitcnt vmcnt(15)
	ds_write_b128 v198, v[2:5]
	s_waitcnt vmcnt(14)
	ds_write_b128 v198, v[6:9] offset:32768
	s_waitcnt vmcnt(13)
	ds_write_b128 v198, v[10:13] offset:8192
	s_waitcnt vmcnt(12)
	ds_write_b128 v198, v[14:17] offset:40960
	s_waitcnt vmcnt(11)
	ds_write_b128 v198, v[18:21] offset:16384
	s_waitcnt vmcnt(10)
	ds_write_b128 v198, v[22:25] offset:49152
	s_waitcnt vmcnt(9)
	ds_write_b128 v198, v[26:29] offset:24576
	s_waitcnt vmcnt(8)
	ds_write_b128 v198, v[30:33] offset:57344
	v_mov_b32_e32 v14, v1
	v_mov_b32_e32 v15, v1
	v_mov_b32_e32 v2, v1
	v_mov_b32_e32 v3, v1
	v_mov_b32_e32 v4, v1
	v_mov_b32_e32 v5, v1
	v_mov_b32_e32 v6, v1
	v_mov_b32_e32 v7, v1
	v_mov_b32_e32 v8, v1
	v_mov_b32_e32 v9, v1
	v_mov_b32_e32 v10, v1
	v_mov_b32_e32 v11, v1
	v_mov_b32_e32 v12, v1
	v_mov_b32_e32 v13, v1
	v_mov_b64_e32 v[30:31], v[14:15]
	v_mov_b64_e32 v[46:47], v[14:15]
	v_mov_b64_e32 v[62:63], v[14:15]
	v_mov_b64_e32 v[78:79], v[14:15]
	v_mov_b64_e32 v[94:95], v[14:15]
	v_mov_b64_e32 v[110:111], v[14:15]
	v_mov_b64_e32 v[126:127], v[14:15]
	v_mov_b64_e32 v[142:143], v[14:15]
	v_mov_b64_e32 v[28:29], v[12:13]
	v_mov_b64_e32 v[26:27], v[10:11]
	v_mov_b64_e32 v[24:25], v[8:9]
	v_mov_b64_e32 v[22:23], v[6:7]
	v_mov_b64_e32 v[20:21], v[4:5]
	v_mov_b64_e32 v[18:19], v[2:3]
	v_mov_b64_e32 v[16:17], v[0:1]
	v_mov_b64_e32 v[44:45], v[12:13]
	v_mov_b64_e32 v[42:43], v[10:11]
	v_mov_b64_e32 v[40:41], v[8:9]
	v_mov_b64_e32 v[38:39], v[6:7]
	v_mov_b64_e32 v[36:37], v[4:5]
	v_mov_b64_e32 v[34:35], v[2:3]
	v_mov_b64_e32 v[32:33], v[0:1]
	v_mov_b64_e32 v[60:61], v[12:13]
	v_mov_b64_e32 v[58:59], v[10:11]
	v_mov_b64_e32 v[56:57], v[8:9]
	v_mov_b64_e32 v[54:55], v[6:7]
	v_mov_b64_e32 v[52:53], v[4:5]
	v_mov_b64_e32 v[50:51], v[2:3]
	v_mov_b64_e32 v[48:49], v[0:1]
	v_mov_b64_e32 v[76:77], v[12:13]
	v_mov_b64_e32 v[74:75], v[10:11]
	v_mov_b64_e32 v[72:73], v[8:9]
	v_mov_b64_e32 v[70:71], v[6:7]
	v_mov_b64_e32 v[68:69], v[4:5]
	v_mov_b64_e32 v[66:67], v[2:3]
	v_mov_b64_e32 v[64:65], v[0:1]
	v_mov_b64_e32 v[92:93], v[12:13]
	v_mov_b64_e32 v[90:91], v[10:11]
	v_mov_b64_e32 v[88:89], v[8:9]
	v_mov_b64_e32 v[86:87], v[6:7]
	v_mov_b64_e32 v[84:85], v[4:5]
	v_mov_b64_e32 v[82:83], v[2:3]
	v_mov_b64_e32 v[80:81], v[0:1]
	v_mov_b64_e32 v[108:109], v[12:13]
	v_mov_b64_e32 v[106:107], v[10:11]
	v_mov_b64_e32 v[104:105], v[8:9]
	v_mov_b64_e32 v[102:103], v[6:7]
	v_mov_b64_e32 v[100:101], v[4:5]
	v_mov_b64_e32 v[98:99], v[2:3]
	v_mov_b64_e32 v[96:97], v[0:1]
	v_mov_b64_e32 v[124:125], v[12:13]
	v_mov_b64_e32 v[122:123], v[10:11]
	v_mov_b64_e32 v[120:121], v[8:9]
	v_mov_b64_e32 v[118:119], v[6:7]
	v_mov_b64_e32 v[116:117], v[4:5]
	v_mov_b64_e32 v[114:115], v[2:3]
	v_mov_b64_e32 v[112:113], v[0:1]
	v_mov_b64_e32 v[140:141], v[12:13]
	v_mov_b64_e32 v[138:139], v[10:11]
	v_mov_b64_e32 v[136:137], v[8:9]
	v_mov_b64_e32 v[134:135], v[6:7]
	v_mov_b64_e32 v[132:133], v[4:5]
	v_mov_b64_e32 v[130:131], v[2:3]
	v_mov_b64_e32 v[128:129], v[0:1]
	s_waitcnt lgkmcnt(0)
	s_barrier
	s_branch .LBB0_109
	.p2align 8

.LBB0_337:
	s_or_b64 exec, exec, s[42:43]
	global_load_dwordx4 v[172:175], v[44:45], off offset:128
	v_lshlrev_b32_e32 v0, 7, v193
	v_and_b32_e32 v2, 0xf80, v0
	v_bfe_u32 v3, v193, 1, 3
	v_lshrrev_b32_e32 v192, 5, v193
	v_and_b32_e32 v0, 0x6f80, v0
	v_bfe_u32 v196, v193, 5, 1
	v_or_b32_e32 v199, 0x8000, v0
	v_bitop3_b32 v0, v192, v3, 1 bitop3:0x6c
	v_lshlrev_b32_e32 v201, 4, v0
	v_bitop3_b32 v0, v196, v3, 2 bitop3:0x36
	s_add_u32 s20, s20, s48
	v_ashrrev_i32_e32 v197, 8, v193
	v_lshlrev_b32_e32 v202, 4, v0
	v_bitop3_b32 v0, v196, v3, 4 bitop3:0x36
	s_addc_u32 s21, s21, s49
	v_lshl_or_b32 v198, v197, 14, v2
	v_lshlrev_b32_e32 v203, 4, v0
	v_bitop3_b32 v0, v196, v3, 6 bitop3:0x36
	v_add_u32_e32 v2, v47, v46
	s_add_u32 s20, s20, 0x100
	v_lshlrev_b32_e32 v204, 4, v0
	v_add_u32_e32 v0, 0x60000, v2
	s_addc_u32 s21, s21, 0
	v_add_u32_e32 v4, 0x40000, v2
	v_mov_b32_e32 v5, v1
	v_add_u32_e32 v6, 0x20000, v2
	v_mov_b32_e32 v7, v1
	v_mov_b32_e32 v3, v1
	v_lshl_add_u64 v[176:177], s[20:21], 0, v[0:1]
	v_lshl_add_u64 v[178:179], s[20:21], 0, v[4:5]
	v_lshl_add_u64 v[180:181], s[20:21], 0, v[6:7]
	v_lshl_add_u64 v[182:183], s[20:21], 0, v[2:3]
	s_mul_i32 s21, s26, 0xfe
	s_mul_i32 s20, s90, 0xfe
	s_mul_i32 s21, s21, s79
	s_sub_i32 s20, s20, s21
	s_add_i32 s20, s20, -2
	s_ashr_i32 s21, s20, 31
	s_add_u32 s20, s67, s20
	s_addc_u32 s21, s91, s21
	s_movk_i32 s4, 0x100
	s_lshl_b64 s[20:21], s[20:21], 11
	v_cmp_gt_u32_e32 vcc, s4, v193
	s_add_u32 s20, s73, s20
	v_readlane_b32 s4, v254, 40
	s_addc_u32 s21, s4, s21
	v_mov_b32_e32 v14, v1
	v_mov_b32_e32 v15, v1
	v_lshl_add_u64 v[184:185], s[20:21], 0, v[0:1]
	v_lshl_add_u64 v[186:187], s[20:21], 0, v[4:5]
	v_lshl_add_u64 v[188:189], s[20:21], 0, v[6:7]
	v_lshl_add_u64 v[190:191], s[20:21], 0, v[2:3]
	v_mov_b32_e32 v0, v1
	v_mov_b32_e32 v2, v1
	v_mov_b32_e32 v4, v1
	v_mov_b32_e32 v6, v1
	v_mov_b32_e32 v8, v1
	v_mov_b32_e32 v9, v1
	v_mov_b32_e32 v10, v1
	v_mov_b32_e32 v11, v1
	v_mov_b32_e32 v12, v1
	v_mov_b32_e32 v13, v1
	v_mov_b64_e32 v[30:31], v[14:15]
	v_mov_b64_e32 v[46:47], v[14:15]
	v_mov_b64_e32 v[62:63], v[14:15]
	v_mov_b64_e32 v[78:79], v[14:15]
	v_mov_b64_e32 v[94:95], v[14:15]
	v_mov_b64_e32 v[110:111], v[14:15]
	v_mov_b64_e32 v[126:127], v[14:15]
	v_mov_b64_e32 v[142:143], v[14:15]
	v_cmp_lt_u32_e64 s[44:45], s76, v193
	v_cmp_eq_u32_e64 s[42:43], 1, v197
	v_cmp_ne_u32_e64 s[46:47], 1, v197
	s_mov_b64 s[20:21], 0
	s_mov_b32 s29, 0
	v_mov_b64_e32 v[28:29], v[12:13]
	v_mov_b64_e32 v[26:27], v[10:11]
	v_mov_b64_e32 v[24:25], v[8:9]
	v_mov_b64_e32 v[22:23], v[6:7]
	v_mov_b64_e32 v[20:21], v[4:5]
	v_mov_b64_e32 v[18:19], v[2:3]
	v_mov_b64_e32 v[16:17], v[0:1]
	v_mov_b64_e32 v[44:45], v[12:13]
	v_mov_b64_e32 v[42:43], v[10:11]
	v_mov_b64_e32 v[40:41], v[8:9]
	v_mov_b64_e32 v[38:39], v[6:7]
	v_mov_b64_e32 v[36:37], v[4:5]
	v_mov_b64_e32 v[34:35], v[2:3]
	v_mov_b64_e32 v[32:33], v[0:1]
	v_mov_b64_e32 v[60:61], v[12:13]
	v_mov_b64_e32 v[58:59], v[10:11]
	v_mov_b64_e32 v[56:57], v[8:9]
	v_mov_b64_e32 v[54:55], v[6:7]
	v_mov_b64_e32 v[52:53], v[4:5]
	v_mov_b64_e32 v[50:51], v[2:3]
	v_mov_b64_e32 v[48:49], v[0:1]
	v_mov_b64_e32 v[76:77], v[12:13]
	v_mov_b64_e32 v[74:75], v[10:11]
	v_mov_b64_e32 v[72:73], v[8:9]
	v_mov_b64_e32 v[70:71], v[6:7]
	v_mov_b64_e32 v[68:69], v[4:5]
	v_mov_b64_e32 v[66:67], v[2:3]
	v_mov_b64_e32 v[64:65], v[0:1]
	v_mov_b64_e32 v[92:93], v[12:13]
	v_mov_b64_e32 v[90:91], v[10:11]
	v_mov_b64_e32 v[88:89], v[8:9]
	v_mov_b64_e32 v[86:87], v[6:7]
	v_mov_b64_e32 v[84:85], v[4:5]
	v_mov_b64_e32 v[82:83], v[2:3]
	v_mov_b64_e32 v[80:81], v[0:1]
	v_mov_b64_e32 v[108:109], v[12:13]
	v_mov_b64_e32 v[106:107], v[10:11]
	v_mov_b64_e32 v[104:105], v[8:9]
	v_mov_b64_e32 v[102:103], v[6:7]
	v_mov_b64_e32 v[100:101], v[4:5]
	v_mov_b64_e32 v[98:99], v[2:3]
	v_mov_b64_e32 v[96:97], v[0:1]
	v_mov_b64_e32 v[124:125], v[12:13]
	v_mov_b64_e32 v[122:123], v[10:11]
	v_mov_b64_e32 v[120:121], v[8:9]
	v_mov_b64_e32 v[118:119], v[6:7]
	v_mov_b64_e32 v[116:117], v[4:5]
	v_mov_b64_e32 v[114:115], v[2:3]
	v_mov_b64_e32 v[112:113], v[0:1]
	v_mov_b64_e32 v[140:141], v[12:13]
	v_mov_b64_e32 v[138:139], v[10:11]
	v_mov_b64_e32 v[136:137], v[8:9]
	v_mov_b64_e32 v[134:135], v[6:7]
	v_mov_b64_e32 v[132:133], v[4:5]
	v_mov_b64_e32 v[130:131], v[2:3]
	v_mov_b64_e32 v[128:129], v[0:1]
	s_mov_b32 s79, 0
	s_waitcnt lgkmcnt(0)
	s_barrier
	s_branch .LBB0_339
	.p2align 8

.LBB0_477:
	s_load_dwordx16 s[4:19], s[0:1], 0xa8
	s_lshl_b32 s88, s21, 8
	s_ashr_i32 s21, s20, 31
	v_mov_b32_e32 v201, v206
	s_lshl_b64 s[20:21], s[20:21], 11
	s_waitcnt lgkmcnt(0)
	s_add_u32 s40, s16, s20
	v_ashrrev_i32_e32 v3, 3, v201
	v_lshlrev_b32_e32 v0, 4, v201
	v_lshlrev_b32_e32 v2, 11, v3
	s_movk_i32 s5, 0x70
	s_addc_u32 s41, s17, s21
	v_and_or_b32 v0, v0, s5, v2
	global_load_dwordx4 v[4:7], v0, s[40:41]
	v_add_u32_e32 v36, 0x20000, v0
	global_load_dwordx4 v[8:11], v36, s[40:41]
	v_add_u32_e32 v38, 0x40000, v0
	global_load_dwordx4 v[12:15], v38, s[40:41]
	s_ashr_i32 s89, s88, 31
	s_lshl_b64 s[48:49], s[88:89], 11
	s_add_u32 s42, s46, s48
	v_add_u32_e32 v40, 0x60000, v0
	s_addc_u32 s43, s47, s49
	global_load_dwordx4 v[16:19], v40, s[40:41]
	global_load_dwordx4 v[20:23], v0, s[42:43]
	global_load_dwordx4 v[24:27], v36, s[42:43]
	global_load_dwordx4 v[28:31], v38, s[42:43]
	global_load_dwordx4 v[32:35], v40, s[42:43]
	global_load_dwordx4 v[144:147], v0, s[40:41] offset:128
	global_load_dwordx4 v[148:151], v36, s[40:41] offset:128
	global_load_dwordx4 v[156:159], v38, s[40:41] offset:128
	global_load_dwordx4 v[168:171], v40, s[40:41] offset:128
	global_load_dwordx4 v[152:155], v0, s[42:43] offset:128
	global_load_dwordx4 v[160:163], v36, s[42:43] offset:128
	global_load_dwordx4 v[164:167], v38, s[42:43] offset:128
	global_load_dwordx4 v[172:175], v40, s[42:43] offset:128
	v_lshlrev_b32_e32 v49, 7, v3
	v_lshrrev_b32_e32 v3, 1, v3
	s_movk_i32 s4, 0x100
	v_xor_b32_e32 v3, v3, v201
	s_add_u32 s48, s91, s48
	v_cmp_gt_u32_e64 s[42:43], s4, v201
	v_lshlrev_b32_e32 v3, 4, v3
	s_addc_u32 s49, s80, s49
	v_readlane_b32 s4, v254, 41
	v_lshlrev_b32_e32 v43, 7, v201
	v_bfe_u32 v44, v201, 1, 3
	v_lshrrev_b32_e32 v229, 5, v201
	v_bfe_u32 v204, v201, 5, 1
	v_and_or_b32 v198, v3, s5, v49
	s_add_u32 s20, s4, s20
	v_readlane_b32 s4, v254, 42
	v_mov_b32_e32 v37, v1
	v_mov_b32_e32 v39, v1
	v_mov_b32_e32 v41, v1
	v_ashrrev_i32_e32 v42, 8, v201
	v_and_b32_e32 v45, 0xf80, v43
	v_and_b32_e32 v43, 0x6f80, v43
	v_bitop3_b32 v46, v229, v44, 1 bitop3:0x6c
	v_bitop3_b32 v47, v204, v44, 2 bitop3:0x36
	v_bitop3_b32 v48, v204, v44, 4 bitop3:0x36
	v_bitop3_b32 v44, v204, v44, 6 bitop3:0x36
	s_addc_u32 s21, s4, s21
	v_mov_b32_e32 v2, v1
	v_cmp_eq_u32_e64 s[40:41], 1, v42
	v_cmp_ne_u32_e64 s[44:45], 1, v42
	v_lshl_or_b32 v192, v42, 14, v45
	v_or_b32_e32 v193, 0x8000, v43
	v_lshlrev_b32_e32 v194, 4, v46
	v_lshlrev_b32_e32 v195, 4, v47
	v_lshlrev_b32_e32 v196, 4, v48
	v_lshlrev_b32_e32 v197, 4, v44
	v_lshl_add_u64 v[176:177], s[48:49], 0, v[40:41]
	v_lshl_add_u64 v[178:179], s[48:49], 0, v[38:39]
	v_lshl_add_u64 v[180:181], s[48:49], 0, v[36:37]
	v_lshl_add_u64 v[182:183], s[48:49], 0, v[0:1]
	v_lshl_add_u64 v[184:185], s[20:21], 0, v[40:41]
	v_lshl_add_u64 v[186:187], s[20:21], 0, v[38:39]
	v_lshl_add_u64 v[188:189], s[20:21], 0, v[36:37]
	v_lshl_add_u64 v[190:191], s[20:21], 0, v[0:1]
	v_mov_b32_e32 v0, v1
	v_mov_b32_e32 v3, v1
	v_cmp_lt_u32_e32 vcc, s73, v201
	s_mov_b64 s[20:21], 0
	s_mov_b32 s65, 0
	s_mov_b32 s72, 0
	s_waitcnt vmcnt(15)
	ds_write_b128 v198, v[4:7]
	s_waitcnt vmcnt(14)
	ds_write_b128 v198, v[8:11] offset:8192
	s_waitcnt vmcnt(13)
	ds_write_b128 v198, v[12:15] offset:16384
	s_waitcnt vmcnt(12)
	ds_write_b128 v198, v[16:19] offset:24576
	s_waitcnt vmcnt(11)
	ds_write_b128 v198, v[20:23] offset:32768
	s_waitcnt vmcnt(10)
	ds_write_b128 v198, v[24:27] offset:40960
	s_waitcnt vmcnt(9)
	ds_write_b128 v198, v[28:31] offset:49152
	s_waitcnt vmcnt(8)
	ds_write_b128 v198, v[32:35] offset:57344
	v_mov_b32_e32 v14, v1
	v_mov_b32_e32 v15, v1
	v_mov_b32_e32 v4, v1
	v_mov_b32_e32 v5, v1
	v_mov_b32_e32 v6, v1
	v_mov_b32_e32 v7, v1
	v_mov_b32_e32 v8, v1
	v_mov_b32_e32 v9, v1
	v_mov_b32_e32 v10, v1
	v_mov_b32_e32 v11, v1
	v_mov_b32_e32 v12, v1
	v_mov_b32_e32 v13, v1
	v_mov_b64_e32 v[30:31], v[14:15]
	v_mov_b64_e32 v[46:47], v[14:15]
	v_mov_b64_e32 v[62:63], v[14:15]
	v_mov_b64_e32 v[78:79], v[14:15]
	v_mov_b64_e32 v[94:95], v[14:15]
	v_mov_b64_e32 v[110:111], v[14:15]
	v_mov_b64_e32 v[126:127], v[14:15]
	v_mov_b64_e32 v[142:143], v[14:15]
	v_mov_b64_e32 v[28:29], v[12:13]
	v_mov_b64_e32 v[26:27], v[10:11]
	v_mov_b64_e32 v[24:25], v[8:9]
	v_mov_b64_e32 v[22:23], v[6:7]
	v_mov_b64_e32 v[20:21], v[4:5]
	v_mov_b64_e32 v[18:19], v[2:3]
	v_mov_b64_e32 v[16:17], v[0:1]
	v_mov_b64_e32 v[44:45], v[12:13]
	v_mov_b64_e32 v[42:43], v[10:11]
	v_mov_b64_e32 v[40:41], v[8:9]
	v_mov_b64_e32 v[38:39], v[6:7]
	v_mov_b64_e32 v[36:37], v[4:5]
	v_mov_b64_e32 v[34:35], v[2:3]
	v_mov_b64_e32 v[32:33], v[0:1]
	v_mov_b64_e32 v[60:61], v[12:13]
	v_mov_b64_e32 v[58:59], v[10:11]
	v_mov_b64_e32 v[56:57], v[8:9]
	v_mov_b64_e32 v[54:55], v[6:7]
	v_mov_b64_e32 v[52:53], v[4:5]
	v_mov_b64_e32 v[50:51], v[2:3]
	v_mov_b64_e32 v[48:49], v[0:1]
	v_mov_b64_e32 v[76:77], v[12:13]
	v_mov_b64_e32 v[74:75], v[10:11]
	v_mov_b64_e32 v[72:73], v[8:9]
	v_mov_b64_e32 v[70:71], v[6:7]
	v_mov_b64_e32 v[68:69], v[4:5]
	v_mov_b64_e32 v[66:67], v[2:3]
	v_mov_b64_e32 v[64:65], v[0:1]
	v_mov_b64_e32 v[92:93], v[12:13]
	v_mov_b64_e32 v[90:91], v[10:11]
	v_mov_b64_e32 v[88:89], v[8:9]
	v_mov_b64_e32 v[86:87], v[6:7]
	v_mov_b64_e32 v[84:85], v[4:5]
	v_mov_b64_e32 v[82:83], v[2:3]
	v_mov_b64_e32 v[80:81], v[0:1]
	v_mov_b64_e32 v[108:109], v[12:13]
	v_mov_b64_e32 v[106:107], v[10:11]
	v_mov_b64_e32 v[104:105], v[8:9]
	v_mov_b64_e32 v[102:103], v[6:7]
	v_mov_b64_e32 v[100:101], v[4:5]
	v_mov_b64_e32 v[98:99], v[2:3]
	v_mov_b64_e32 v[96:97], v[0:1]
	v_mov_b64_e32 v[124:125], v[12:13]
	v_mov_b64_e32 v[122:123], v[10:11]
	v_mov_b64_e32 v[120:121], v[8:9]
	v_mov_b64_e32 v[118:119], v[6:7]
	v_mov_b64_e32 v[116:117], v[4:5]
	v_mov_b64_e32 v[114:115], v[2:3]
	v_mov_b64_e32 v[112:113], v[0:1]
	v_mov_b64_e32 v[140:141], v[12:13]
	v_mov_b64_e32 v[138:139], v[10:11]
	v_mov_b64_e32 v[136:137], v[8:9]
	v_mov_b64_e32 v[134:135], v[6:7]
	v_mov_b64_e32 v[132:133], v[4:5]
	v_mov_b64_e32 v[130:131], v[2:3]
	v_mov_b64_e32 v[128:129], v[0:1]
	s_waitcnt lgkmcnt(0)
	s_barrier
	s_branch .LBB0_479
	.p2align 8

.LBB0_543:
	s_and_b32 s26, s42, 7
	v_mov_b32_e32 v146, v206
	s_mulk_i32 s26, 0x900
	v_bfe_u32 v148, v146, 6, 2
	s_lshl_b32 s20, s23, 7
	s_load_dwordx16 s[4:19], s[0:1], 0xa8
	v_and_b32_e32 v12, 31, v146
	s_add_i32 s40, s20, s26
	v_lshlrev_b32_e32 v0, 5, v148
	v_or3_b32 v134, v0, s40, v12
	v_ashrrev_i32_e32 v149, 8, v146
	s_lshl_b32 s28, s22, 7
	v_ashrrev_i32_e32 v135, 31, v134
	v_lshl_add_u32 v2, v149, 6, s28
	v_lshlrev_b64 v[4:5], 12, v[134:135]
	v_bfe_u32 v145, v146, 5, 1
	s_waitcnt lgkmcnt(0)
	v_lshl_add_u64 v[4:5], s[12:13], 0, v[4:5]
	v_ashrrev_i32_e32 v3, 31, v2
	v_lshl_add_u64 v[2:3], v[2:3], 1, v[4:5]
	v_lshlrev_b32_e32 v0, 4, v145
	v_lshl_add_u64 v[2:3], v[2:3], 0, v[0:1]
	global_load_dwordx4 v[98:101], v[2:3], off
	global_load_dwordx4 v[102:105], v[2:3], off offset:32
	global_load_dwordx4 v[106:109], v[2:3], off offset:64
	global_load_dwordx4 v[110:113], v[2:3], off offset:96
	v_and_b32_e32 v2, 3, v146
	v_lshlrev_b32_e32 v3, 1, v146
	v_and_or_b32 v13, v3, 8, v2
	v_ashrrev_i32_e32 v2, 31, v146
	v_lshrrev_b32_e32 v2, 28, v2
	v_add_u32_e32 v18, v146, v2
	s_ashr_i32 s29, s28, 31
	v_ashrrev_i32_e32 v150, 4, v18
	s_lshl_b64 s[20:21], s[28:29], 1
	v_add_u32_e32 v2, s26, v150
	v_lshlrev_b32_e32 v4, 7, v150
	v_lshlrev_b32_e32 v5, 3, v146
	s_add_u32 s20, s12, s20
	v_ashrrev_i32_e32 v3, 31, v2
	v_sub_u32_e32 v4, v5, v4
	s_addc_u32 s21, s13, s21
	v_lshlrev_b64 v[2:3], 12, v[2:3]
	v_ashrrev_i32_e32 v5, 31, v4
	v_lshl_add_u64 v[2:3], s[20:21], 0, v[2:3]
	v_lshlrev_b64 v[4:5], 1, v[4:5]
	v_lshl_add_u64 v[2:3], v[2:3], 0, v[4:5]
	v_add_u32_e32 v19, 0x200, v146
	global_load_dwordx4 v[114:117], v[2:3], off offset:2048
	v_ashrrev_i32_e32 v2, 31, v19
	v_lshrrev_b32_e32 v2, 28, v2
	v_add_u32_e32 v20, v19, v2
	v_ashrrev_i32_e32 v151, 4, v20
	v_add_u32_e32 v2, s26, v151
	v_lshlrev_b32_e32 v6, 7, v151
	v_lshlrev_b32_e32 v7, 3, v19
	v_ashrrev_i32_e32 v3, 31, v2
	v_sub_u32_e32 v6, v7, v6
	s_mul_i32 s22, s22, 0x480000
	v_lshlrev_b64 v[2:3], 12, v[2:3]
	v_ashrrev_i32_e32 v7, 31, v6
	s_mul_hi_i32 s27, s28, 0x9000
	s_add_u32 s30, s14, s22
	v_lshl_add_u64 v[2:3], s[20:21], 0, v[2:3]
	v_lshlrev_b64 v[6:7], 1, v[6:7]
	s_addc_u32 s31, s15, s27
	v_lshl_add_u64 v[2:3], v[2:3], 0, v[6:7]
	s_lshl_b32 s22, s26, 1
	global_load_dwordx4 v[118:121], v[2:3], off offset:2048
	v_ashrrev_i32_e32 v21, 3, v146
	v_mov_b64_e32 v[2:3], s[30:31]
	s_mov_b32 s4, 0x9000
	s_cmp_lt_i32 s23, 2
	v_mad_i64_i32 v[8:9], s[30:31], v21, s4, v[2:3]
	s_mov_b32 s23, s52
	v_lshlrev_b32_e32 v10, 4, v146
	v_lshl_add_u64 v[8:9], v[8:9], 0, s[22:23]
	v_and_b32_e32 v10, 0x70, v10
	v_mov_b32_e32 v11, v1
	v_lshl_add_u64 v[136:137], v[8:9], 0, v[10:11]
	v_ashrrev_i32_e32 v8, 3, v19
	v_mad_i64_i32 v[2:3], s[30:31], v8, s4, v[2:3]
	v_lshl_add_u64 v[2:3], v[2:3], 0, s[22:23]
	v_lshl_add_u64 v[138:139], v[2:3], 0, v[10:11]
	global_load_dwordx4 v[122:125], v[136:137], off
	global_load_dwordx4 v[126:129], v[138:139], off
	v_and_b32_e32 v2, 0xffffff0, v18
	v_sub_u32_e32 v2, v146, v2
	v_lshlrev_b32_e32 v3, 8, v150
	v_bitop3_b32 v2, v2, v150, 15 bitop3:0x78
	v_lshl_add_u32 v152, v2, 4, v3
	v_and_b32_e32 v2, 0xffffff0, v20
	v_sub_u32_e32 v2, v19, v2
	v_lshlrev_b32_e32 v3, 8, v151
	v_bitop3_b32 v2, v2, v151, 15 bitop3:0x78
	v_lshl_add_u32 v153, v2, 4, v3
	v_lshrrev_b32_e32 v3, 1, v21
	v_xor_b32_e32 v3, v3, v146
	v_lshlrev_b32_e32 v2, 7, v21
	v_lshlrev_b32_e32 v3, 4, v3
	s_movk_i32 s4, 0x70
	v_and_or_b32 v154, v3, s4, v2
	v_lshrrev_b32_e32 v3, 1, v8
	v_xor_b32_e32 v3, v3, v146
	v_lshrrev_b32_e32 v14, 1, v146
	v_lshlrev_b32_e32 v2, 7, v8
	v_lshlrev_b32_e32 v3, 4, v3
	v_and_b32_e32 v15, 4, v14
	v_and_or_b32 v155, v3, s4, v2
	v_lshl_add_u64 v[140:141], s[20:21], 0, v[4:5]
	v_lshl_or_b32 v2, v149, 3, v145
	v_mov_b32_e32 v4, 0x6000
	v_or_b32_e32 v16, v13, v15
	v_lshl_or_b32 v157, v12, 7, v4
	v_bitop3_b32 v4, v13, v2, v15 bitop3:0x36
	v_lshlrev_b32_e32 v158, 4, v4
	v_bitop3_b32 v4, v2, v16, 2 bitop3:0x36
	v_lshlrev_b32_e32 v159, 4, v4
	v_bitop3_b32 v4, v2, v16, 4 bitop3:0x36
	v_bitop3_b32 v2, v2, v16, 6 bitop3:0x36
	v_bfe_u32 v3, v146, 1, 3
	v_lshlrev_b32_e32 v161, 4, v2
	v_bitop3_b32 v2, v145, v14, 7 bitop3:0x78
	v_lshlrev_b32_e32 v162, 4, v2
	v_bitop3_b32 v2, v145, v3, 2 bitop3:0x36
	v_lshlrev_b32_e32 v163, 4, v2
	v_bitop3_b32 v2, v145, v3, 4 bitop3:0x36
	v_and_or_b32 v17, v146, 16, v16
	v_lshlrev_b32_e32 v164, 4, v2
	v_bitop3_b32 v2, v145, v3, 6 bitop3:0x36
	v_mov_b32_e32 v50, v1
	v_mov_b32_e32 v51, v1
	v_lshl_add_u64 v[142:143], s[20:21], 0, v[6:7]
	v_lshlrev_b32_e32 v156, 8, v17
	v_lshlrev_b32_e32 v160, 4, v4
	v_lshlrev_b32_e32 v165, 4, v2
	v_mov_b32_e32 v52, v1
	v_mov_b32_e32 v53, v1
	v_mov_b32_e32 v54, v1
	v_mov_b32_e32 v55, v1
	v_mov_b32_e32 v56, v1
	v_mov_b32_e32 v57, v1
	v_mov_b32_e32 v58, v1
	v_mov_b32_e32 v59, v1
	v_mov_b32_e32 v60, v1
	v_mov_b32_e32 v61, v1
	v_mov_b32_e32 v62, v1
	v_mov_b32_e32 v63, v1
	v_mov_b32_e32 v64, v1
	v_mov_b32_e32 v65, v1
	v_mov_b64_e32 v[34:35], v[50:51]
	v_mov_b64_e32 v[18:19], v[50:51]
	v_mov_b64_e32 v[2:3], v[50:51]
	v_and_b32_e32 v147, 63, v146
	s_cselect_b32 s27, 4, 36
	s_cselect_b32 s22, -3, 1
	s_mov_b32 s30, 0
	v_mov_b32_e32 v166, 0
	v_mov_b32_e32 v130, 0xf149f2ca
	v_mov_b64_e32 v[36:37], v[52:53]
	v_mov_b64_e32 v[38:39], v[54:55]
	v_mov_b64_e32 v[40:41], v[56:57]
	v_mov_b64_e32 v[42:43], v[58:59]
	v_mov_b64_e32 v[44:45], v[60:61]
	v_mov_b64_e32 v[46:47], v[62:63]
	v_mov_b64_e32 v[48:49], v[64:65]
	v_mov_b64_e32 v[20:21], v[52:53]
	v_mov_b64_e32 v[22:23], v[54:55]
	v_mov_b64_e32 v[24:25], v[56:57]
	v_mov_b64_e32 v[26:27], v[58:59]
	v_mov_b64_e32 v[28:29], v[60:61]
	v_mov_b64_e32 v[30:31], v[62:63]
	v_mov_b64_e32 v[32:33], v[64:65]
	v_mov_b64_e32 v[4:5], v[52:53]
	v_mov_b64_e32 v[6:7], v[54:55]
	v_mov_b64_e32 v[8:9], v[56:57]
	v_mov_b64_e32 v[10:11], v[58:59]
	v_mov_b64_e32 v[12:13], v[60:61]
	v_mov_b64_e32 v[14:15], v[62:63]
	v_mov_b64_e32 v[16:17], v[64:65]
	s_waitcnt vmcnt(3)
	ds_write_b128 v152, v[114:117]
	s_waitcnt vmcnt(2)
	ds_write_b128 v153, v[118:121]
	s_waitcnt vmcnt(1)
	ds_write_b128 v154, v[122:125] offset:24576
	s_waitcnt vmcnt(0)
	ds_write_b128 v155, v[126:129] offset:24576
	s_waitcnt lgkmcnt(0)
	s_barrier
	.p2align 8

.LBB0_574:
	s_mov_b32 s20, 27
	s_abs_i32 s21, s20
	v_cvt_f32_u32_e32 v0, s21
	s_sub_i32 s23, 0, s21
	s_ashr_i32 s22, s20, 31
	v_mov_b32_e32 v193, v206
	v_rcp_iflag_f32_e32 v0, v0
	v_mov_b32_e32 v35, v1
	v_mov_b32_e32 v37, v1
	v_mov_b32_e32 v39, v1
	v_mul_f32_e32 v0, 0x4f7ffffe, v0
	v_cvt_u32_f32_e32 v0, v0
	s_nop 0
	v_readfirstlane_b32 s28, v0
	s_mul_i32 s23, s23, s28
	s_mul_hi_u32 s23, s28, s23
	s_add_i32 s28, s28, s23
	s_mul_hi_u32 s23, s27, s28
	s_mul_i32 s28, s23, s21
	s_sub_i32 s28, s27, s28
	s_add_i32 s29, s23, 1
	s_sub_i32 s30, s28, s21
	s_cmp_ge_u32 s28, s21
	s_cselect_b32 s23, s29, s23
	s_cselect_b32 s28, s30, s28
	s_add_i32 s29, s23, 1
	s_cmp_ge_u32 s28, s21
	s_cselect_b32 s21, s29, s23
	s_xor_b32 s21, s21, s22
	s_sub_i32 s21, s21, s22
	s_mul_i32 s22, s21, -9
	s_add_i32 s22, s22, 9
	s_min_i32 s22, s22, 9
	s_abs_i32 s23, s22
	v_cvt_f32_u32_e32 v0, s23
	s_sub_i32 s30, 0, s23
	s_mul_i32 s46, s21, s20
	s_sub_i32 s20, s27, s46
	v_rcp_iflag_f32_e32 v0, v0
	s_abs_i32 s28, s20
	s_xor_b32 s29, s20, s22
	s_ashr_i32 s29, s29, 31
	v_mul_f32_e32 v0, 0x4f7ffffe, v0
	v_cvt_u32_f32_e32 v0, v0
	s_load_dwordx16 s[4:19], s[0:1], 0xa8
	s_waitcnt lgkmcnt(0)
	s_load_dwordx2 s[4:5], s[0:1], 0x170
	v_readfirstlane_b32 s31, v0
	s_mul_i32 s30, s30, s31
	s_mul_hi_u32 s30, s31, s30
	s_add_i32 s31, s31, s30
	s_mul_hi_u32 s30, s28, s31
	s_mul_i32 s31, s30, s23
	s_sub_i32 s28, s28, s31
	s_add_i32 s40, s30, 1
	s_sub_i32 s31, s28, s23
	s_cmp_ge_u32 s28, s23
	s_cselect_b32 s30, s40, s30
	s_cselect_b32 s28, s31, s28
	s_add_i32 s31, s30, 1
	s_cmp_ge_u32 s28, s23
	s_cselect_b32 s23, s31, s30
	v_readlane_b32 s28, v254, 8
	s_add_i32 s21, s21, s28
	s_xor_b32 s23, s23, s29
	s_mul_i32 s47, s21, 9
	s_sub_i32 s21, s23, s29
	s_add_i32 s20, s47, s20
	s_mul_i32 s48, s21, s22
	s_sub_i32 s20, s20, s48
	s_lshl_b32 s28, s20, 8
	s_ashr_i32 s29, s28, 31
	s_lshl_b32 s22, s21, 8
	s_lshl_b64 s[20:21], s[28:29], 11
	s_add_u32 s30, s10, s20
	v_lshlrev_b32_e32 v0, 4, v193
	s_addc_u32 s31, s11, s21
	s_ashr_i32 s23, s22, 31
	v_ashrrev_i32_e32 v40, 3, v193
	v_and_b32_e32 v0, 0x70, v0
	s_lshl_b64 s[20:21], s[22:23], 11
	v_lshl_or_b32 v0, v40, 11, v0
	s_waitcnt lgkmcnt(0)
	s_add_u32 s40, s4, s20
	v_add_u32_e32 v34, 0x20000, v0
	v_add_u32_e32 v36, 0x40000, v0
	v_add_u32_e32 v38, 0x60000, v0
	s_addc_u32 s41, s5, s21
	global_load_dwordx4 v[2:5], v0, s[30:31]
	global_load_dwordx4 v[6:9], v34, s[30:31]
	global_load_dwordx4 v[10:13], v36, s[30:31]
	global_load_dwordx4 v[14:17], v38, s[30:31]
	global_load_dwordx4 v[18:21], v0, s[40:41]
	global_load_dwordx4 v[22:25], v34, s[40:41]
	global_load_dwordx4 v[26:29], v36, s[40:41]
	global_load_dwordx4 v[30:33], v38, s[40:41]
	global_load_dwordx4 v[144:147], v0, s[30:31] offset:128
	global_load_dwordx4 v[148:151], v34, s[30:31] offset:128
	global_load_dwordx4 v[156:159], v36, s[30:31] offset:128
	global_load_dwordx4 v[168:171], v38, s[30:31] offset:128
	global_load_dwordx4 v[152:155], v0, s[40:41] offset:128
	global_load_dwordx4 v[160:163], v34, s[40:41] offset:128
	global_load_dwordx4 v[164:167], v36, s[40:41] offset:128
	global_load_dwordx4 v[172:175], v38, s[40:41] offset:128
	v_lshlrev_b32_e32 v48, 7, v40
	v_lshrrev_b32_e32 v40, 1, v40
	s_movk_i32 s4, 0x100
	v_xor_b32_e32 v40, v40, v193
	v_cmp_gt_u32_e64 s[40:41], s4, v193
	v_lshlrev_b32_e32 v40, 4, v40
	s_movk_i32 s4, 0x70
	v_and_or_b32 v201, v40, s4, v48
	v_readlane_b32 s4, v254, 48
	s_add_u32 s20, s4, s20
	v_readlane_b32 s4, v254, 49
	s_addc_u32 s21, s4, s21
	s_add_i32 s27, s27, s47
	v_lshl_add_u64 v[176:177], s[20:21], 0, v[38:39]
	v_lshl_add_u64 v[178:179], s[20:21], 0, v[36:37]
	v_lshl_add_u64 v[180:181], s[20:21], 0, v[34:35]
	v_lshl_add_u64 v[182:183], s[20:21], 0, v[0:1]
	s_sub_i32 s20, s27, s46
	s_sub_i32 s20, s20, s48
	s_lshl_b32 s20, s20, 8
	s_ashr_i32 s21, s20, 31
	s_lshl_b64 s[20:21], s[20:21], 11
	v_readlane_b32 s4, v254, 50
	v_lshlrev_b32_e32 v42, 7, v193
	v_bfe_u32 v43, v193, 1, 3
	v_lshrrev_b32_e32 v192, 5, v193
	v_bfe_u32 v194, v193, 5, 1
	s_add_u32 s20, s4, s20
	v_readlane_b32 s4, v254, 51
	v_ashrrev_i32_e32 v41, 8, v193
	v_and_b32_e32 v44, 0xf80, v42
	v_and_b32_e32 v42, 0x6f80, v42
	v_bitop3_b32 v45, v192, v43, 1 bitop3:0x6c
	v_bitop3_b32 v46, v194, v43, 2 bitop3:0x36
	v_bitop3_b32 v47, v194, v43, 4 bitop3:0x36
	v_bitop3_b32 v43, v194, v43, 6 bitop3:0x36
	s_addc_u32 s21, s4, s21
	v_cmp_eq_u32_e32 vcc, 1, v41
	v_cmp_ne_u32_e64 s[44:45], 1, v41
	v_lshl_or_b32 v195, v41, 14, v44
	v_or_b32_e32 v196, 0x8000, v42
	v_lshlrev_b32_e32 v197, 4, v45
	v_lshlrev_b32_e32 v198, 4, v46
	v_lshlrev_b32_e32 v199, 4, v47
	v_lshlrev_b32_e32 v200, 4, v43
	v_lshl_add_u64 v[184:185], s[20:21], 0, v[38:39]
	v_lshl_add_u64 v[186:187], s[20:21], 0, v[36:37]
	v_lshl_add_u64 v[188:189], s[20:21], 0, v[34:35]
	v_lshl_add_u64 v[190:191], s[20:21], 0, v[0:1]
	v_mov_b32_e32 v0, v1
	v_cmp_lt_u32_e64 s[42:43], s66, v193
	s_mov_b64 s[20:21], 0
	s_mov_b32 s27, 0
	s_mov_b32 s29, 0
	s_waitcnt vmcnt(15)
	ds_write_b128 v201, v[2:5]
	s_waitcnt vmcnt(14)
	ds_write_b128 v201, v[6:9] offset:8192
	s_waitcnt vmcnt(13)
	ds_write_b128 v201, v[10:13] offset:16384
	s_waitcnt vmcnt(12)
	ds_write_b128 v201, v[14:17] offset:24576
	s_waitcnt vmcnt(11)
	ds_write_b128 v201, v[18:21] offset:32768
	s_waitcnt vmcnt(10)
	ds_write_b128 v201, v[22:25] offset:40960
	s_waitcnt vmcnt(9)
	ds_write_b128 v201, v[26:29] offset:49152
	s_waitcnt vmcnt(8)
	ds_write_b128 v201, v[30:33] offset:57344
	v_mov_b32_e32 v14, v1
	v_mov_b32_e32 v15, v1
	v_mov_b32_e32 v2, v1
	v_mov_b32_e32 v3, v1
	v_mov_b32_e32 v4, v1
	v_mov_b32_e32 v5, v1
	v_mov_b32_e32 v6, v1
	v_mov_b32_e32 v7, v1
	v_mov_b32_e32 v8, v1
	v_mov_b32_e32 v9, v1
	v_mov_b32_e32 v10, v1
	v_mov_b32_e32 v11, v1
	v_mov_b32_e32 v12, v1
	v_mov_b32_e32 v13, v1
	v_mov_b64_e32 v[30:31], v[14:15]
	v_mov_b64_e32 v[46:47], v[14:15]
	v_mov_b64_e32 v[62:63], v[14:15]
	v_mov_b64_e32 v[78:79], v[14:15]
	v_mov_b64_e32 v[94:95], v[14:15]
	v_mov_b64_e32 v[110:111], v[14:15]
	v_mov_b64_e32 v[126:127], v[14:15]
	v_mov_b64_e32 v[142:143], v[14:15]
	v_mov_b64_e32 v[28:29], v[12:13]
	v_mov_b64_e32 v[26:27], v[10:11]
	v_mov_b64_e32 v[24:25], v[8:9]
	v_mov_b64_e32 v[22:23], v[6:7]
	v_mov_b64_e32 v[20:21], v[4:5]
	v_mov_b64_e32 v[18:19], v[2:3]
	v_mov_b64_e32 v[16:17], v[0:1]
	v_mov_b64_e32 v[44:45], v[12:13]
	v_mov_b64_e32 v[42:43], v[10:11]
	v_mov_b64_e32 v[40:41], v[8:9]
	v_mov_b64_e32 v[38:39], v[6:7]
	v_mov_b64_e32 v[36:37], v[4:5]
	v_mov_b64_e32 v[34:35], v[2:3]
	v_mov_b64_e32 v[32:33], v[0:1]
	v_mov_b64_e32 v[60:61], v[12:13]
	v_mov_b64_e32 v[58:59], v[10:11]
	v_mov_b64_e32 v[56:57], v[8:9]
	v_mov_b64_e32 v[54:55], v[6:7]
	v_mov_b64_e32 v[52:53], v[4:5]
	v_mov_b64_e32 v[50:51], v[2:3]
	v_mov_b64_e32 v[48:49], v[0:1]
	v_mov_b64_e32 v[76:77], v[12:13]
	v_mov_b64_e32 v[74:75], v[10:11]
	v_mov_b64_e32 v[72:73], v[8:9]
	v_mov_b64_e32 v[70:71], v[6:7]
	v_mov_b64_e32 v[68:69], v[4:5]
	v_mov_b64_e32 v[66:67], v[2:3]
	v_mov_b64_e32 v[64:65], v[0:1]
	v_mov_b64_e32 v[92:93], v[12:13]
	v_mov_b64_e32 v[90:91], v[10:11]
	v_mov_b64_e32 v[88:89], v[8:9]
	v_mov_b64_e32 v[86:87], v[6:7]
	v_mov_b64_e32 v[84:85], v[4:5]
	v_mov_b64_e32 v[82:83], v[2:3]
	v_mov_b64_e32 v[80:81], v[0:1]
	v_mov_b64_e32 v[108:109], v[12:13]
	v_mov_b64_e32 v[106:107], v[10:11]
	v_mov_b64_e32 v[104:105], v[8:9]
	v_mov_b64_e32 v[102:103], v[6:7]
	v_mov_b64_e32 v[100:101], v[4:5]
	v_mov_b64_e32 v[98:99], v[2:3]
	v_mov_b64_e32 v[96:97], v[0:1]
	v_mov_b64_e32 v[124:125], v[12:13]
	v_mov_b64_e32 v[122:123], v[10:11]
	v_mov_b64_e32 v[120:121], v[8:9]
	v_mov_b64_e32 v[118:119], v[6:7]
	v_mov_b64_e32 v[116:117], v[4:5]
	v_mov_b64_e32 v[114:115], v[2:3]
	v_mov_b64_e32 v[112:113], v[0:1]
	v_mov_b64_e32 v[140:141], v[12:13]
	v_mov_b64_e32 v[138:139], v[10:11]
	v_mov_b64_e32 v[136:137], v[8:9]
	v_mov_b64_e32 v[134:135], v[6:7]
	v_mov_b64_e32 v[132:133], v[4:5]
	v_mov_b64_e32 v[130:131], v[2:3]
	v_mov_b64_e32 v[128:129], v[0:1]
	s_waitcnt lgkmcnt(0)
	s_barrier
	s_branch .LBB0_576
	.p2align 8

.LBB0_596:
	s_cmp_gt_u32 s31, 53
	s_cselect_b64 s[20:21], -1, 0
	s_cmpk_lt_u32 s31, 0x5a
	s_cselect_b32 s26, 1, 2
	s_and_b64 s[22:23], s[20:21], exec
	s_cselect_b32 s48, s26, 0
	s_sub_i32 s22, s31, 54
	s_cmp_lt_u32 s22, 36
	s_cselect_b64 s[22:23], -1, 0
	s_and_b64 s[26:27], s[22:23], exec
	s_movk_i32 s26, 0xffca
	s_cselect_b32 s28, s26, 0xffffffa6
	s_and_b64 s[26:27], s[20:21], exec
	s_mov_b32 s26, 9
	s_cselect_b32 s27, s28, 0
	s_abs_i32 s28, s26
	v_cvt_f32_u32_e32 v0, s28
	s_sub_i32 s42, 0, s28
	s_add_i32 s29, s27, s31
	s_abs_i32 s41, s29
	v_rcp_iflag_f32_e32 v0, v0
	s_xor_b32 s40, s29, s26
	s_ashr_i32 s40, s40, 31
	v_readlane_b32 s4, v254, 46
	v_mul_f32_e32 v0, 0x4f7ffffe, v0
	v_cvt_u32_f32_e32 v0, v0
	s_movk_i32 s45, 0x100
	v_mov_b32_e32 v193, v206
	v_mov_b32_e32 v35, v1
	v_readfirstlane_b32 s43, v0
	s_mul_i32 s42, s42, s43
	s_mul_hi_u32 s42, s43, s42
	s_add_i32 s43, s43, s42
	s_mul_hi_u32 s42, s41, s43
	s_mul_i32 s43, s42, s28
	s_sub_i32 s41, s41, s43
	s_add_i32 s43, s42, 1
	s_sub_i32 s44, s41, s28
	s_cmp_ge_u32 s41, s28
	s_cselect_b32 s42, s43, s42
	s_cselect_b32 s41, s44, s41
	s_add_i32 s43, s42, 1
	s_cmp_ge_u32 s41, s28
	s_cselect_b32 s28, s43, s42
	s_xor_b32 s28, s28, s40
	s_sub_i32 s40, s28, s40
	s_mul_i32 s28, s40, s26
	s_sub_i32 s26, s4, s28
	s_load_dwordx16 s[4:19], s[0:1], 0xa8
	s_add_i32 s29, s26, s29
	s_lshl_b32 s50, s29, 8
	s_lshl_b32 s46, s40, 8
	s_and_b64 s[40:41], s[20:21], exec
	s_cselect_b32 s26, s45, 0x180
	s_ashr_i32 s51, s50, 31
	s_mul_i32 s29, s29, 0x60000
	s_mul_hi_i32 s40, s50, 0x600
	s_waitcnt lgkmcnt(0)
	s_add_u32 s42, s18, s29
	s_addc_u32 s43, s19, s40
	s_and_b64 s[40:41], s[20:21], exec
	s_cselect_b32 s29, 0x180, 0
	s_lshl_b32 s40, s29, 1
	s_add_u32 s40, s42, s40
	s_addc_u32 s41, s43, 0
	s_and_b64 s[22:23], s[22:23], exec
	s_movk_i32 s22, 0x188
	s_cselect_b32 s22, 0x180, s22
	s_and_b64 s[20:21], s[20:21], exec
	s_cselect_b32 s20, s22, 0x178
	s_add_u32 s20, s0, s20
	s_addc_u32 s21, s1, 0
	s_load_dwordx2 s[20:21], s[20:21], 0x0
	s_mul_hi_i32 s23, s46, s26
	s_mul_i32 s22, s46, s26
	s_ashr_i32 s47, s46, 31
	s_lshl_b64 s[22:23], s[22:23], 1
	s_waitcnt lgkmcnt(0)
	s_add_u32 s42, s20, s22
	s_addc_u32 s43, s21, s23
	s_cmp_eq_u32 s48, 2
	s_cselect_b64 s[20:21], -1, 0
	s_and_b64 s[20:21], s[20:21], exec
	s_cselect_b32 s22, s42, s40
	s_cselect_b32 s44, s26, 0x300
	s_cselect_b32 s20, s40, s42
	s_cselect_b32 s40, 0x300, s26
	s_cselect_b32 s23, s43, s41
	v_ashrrev_i32_e32 v48, 3, v193
	v_lshlrev_b32_e32 v0, 4, v193
	v_and_b32_e32 v2, 0x70, v0
	v_mul_lo_u32 v0, s44, v48
	v_mul_lo_u32 v3, s40, v48
	s_cselect_b32 s21, s41, s43
	v_lshl_or_b32 v0, v0, 1, v2
	v_lshl_or_b32 v34, v3, 1, v2
	s_lshl_b32 s41, s44, 7
	s_lshl_b32 s40, s40, 7
	v_add_u32_e32 v36, s41, v0
	v_add_u32_e32 v38, s40, v34
	v_add_u32_e32 v40, s41, v36
	v_add_u32_e32 v42, s40, v38
	v_add_u32_e32 v44, s41, v40
	v_add_u32_e32 v46, s40, v42
	global_load_dwordx4 v[2:5], v0, s[22:23]
	global_load_dwordx4 v[6:9], v34, s[20:21]
	global_load_dwordx4 v[10:13], v36, s[22:23]
	global_load_dwordx4 v[14:17], v38, s[20:21]
	global_load_dwordx4 v[18:21], v40, s[22:23]
	global_load_dwordx4 v[22:25], v42, s[20:21]
	global_load_dwordx4 v[26:29], v44, s[22:23]
	global_load_dwordx4 v[30:33], v46, s[20:21]
	global_load_dwordx4 v[144:147], v0, s[22:23] offset:128
	global_load_dwordx4 v[148:151], v34, s[20:21] offset:128
	global_load_dwordx4 v[152:155], v36, s[22:23] offset:128
	global_load_dwordx4 v[156:159], v38, s[20:21] offset:128
	global_load_dwordx4 v[160:163], v40, s[22:23] offset:128
	global_load_dwordx4 v[164:167], v42, s[20:21] offset:128
	global_load_dwordx4 v[168:171], v44, s[22:23] offset:128
	global_load_dwordx4 v[172:175], v46, s[20:21] offset:128
	s_lshr_b32 s54, s26, 6
	v_lshlrev_b32_e32 v56, 7, v48
	v_lshrrev_b32_e32 v48, 1, v48
	s_lshl_b32 s55, s54, 16
	v_xor_b32_e32 v48, v48, v193
	s_add_u32 s22, s22, 0x100
	v_lshlrev_b32_e32 v48, 4, v48
	s_movk_i32 s4, 0x70
	s_addc_u32 s23, s23, 0
	v_lshlrev_b32_e32 v50, 7, v193
	v_bfe_u32 v51, v193, 1, 3
	v_lshrrev_b32_e32 v192, 5, v193
	v_bfe_u32 v194, v193, 5, 1
	v_and_or_b32 v201, v48, s4, v56
	s_add_u32 s20, s20, 0x100
	v_mov_b32_e32 v37, v1
	v_mov_b32_e32 v39, v1
	v_mov_b32_e32 v41, v1
	v_mov_b32_e32 v43, v1
	v_mov_b32_e32 v45, v1
	v_mov_b32_e32 v47, v1
	v_ashrrev_i32_e32 v49, 8, v193
	v_and_b32_e32 v52, 0xf80, v50
	v_and_b32_e32 v50, 0x6f80, v50
	v_bitop3_b32 v53, v192, v51, 1 bitop3:0x6c
	v_bitop3_b32 v54, v194, v51, 2 bitop3:0x36
	v_bitop3_b32 v55, v194, v51, 4 bitop3:0x36
	v_bitop3_b32 v51, v194, v51, 6 bitop3:0x36
	s_addc_u32 s21, s21, 0
	v_lshl_or_b32 v195, v49, 14, v52
	v_or_b32_e32 v196, 0x8000, v50
	v_lshlrev_b32_e32 v197, 4, v53
	v_lshlrev_b32_e32 v198, 4, v54
	v_lshlrev_b32_e32 v199, 4, v55
	v_lshlrev_b32_e32 v200, 4, v51
	v_cmp_gt_u32_e32 vcc, s45, v193
	v_cmp_eq_u32_e64 s[40:41], 1, v49
	v_cmp_ne_u32_e64 s[44:45], 1, v49
	v_lshl_add_u64 v[176:177], s[22:23], 0, v[0:1]
	s_waitcnt vmcnt(15)
	ds_write_b128 v201, v[2:5]
	s_waitcnt vmcnt(14)
	ds_write_b128 v201, v[6:9] offset:32768
	s_waitcnt vmcnt(13)
	ds_write_b128 v201, v[10:13] offset:8192
	s_waitcnt vmcnt(12)
	ds_write_b128 v201, v[14:17] offset:40960
	s_waitcnt vmcnt(11)
	ds_write_b128 v201, v[18:21] offset:16384
	s_waitcnt vmcnt(10)
	ds_write_b128 v201, v[22:25] offset:49152
	s_waitcnt vmcnt(9)
	ds_write_b128 v201, v[26:29] offset:24576
	s_waitcnt vmcnt(8)
	ds_write_b128 v201, v[30:33] offset:57344
	v_mov_b32_e32 v14, v1
	v_mov_b32_e32 v15, v1
	v_lshl_add_u64 v[178:179], s[22:23], 0, v[36:37]
	v_lshl_add_u64 v[180:181], s[22:23], 0, v[40:41]
	v_lshl_add_u64 v[182:183], s[22:23], 0, v[44:45]
	v_lshl_add_u64 v[184:185], s[20:21], 0, v[34:35]
	v_lshl_add_u64 v[186:187], s[20:21], 0, v[38:39]
	v_lshl_add_u64 v[188:189], s[20:21], 0, v[42:43]
	v_lshl_add_u64 v[190:191], s[20:21], 0, v[46:47]
	v_mov_b32_e32 v0, v1
	v_mov_b32_e32 v2, v1
	v_mov_b32_e32 v3, v1
	v_mov_b32_e32 v4, v1
	v_mov_b32_e32 v5, v1
	v_mov_b32_e32 v6, v1
	v_mov_b32_e32 v7, v1
	v_mov_b32_e32 v8, v1
	v_mov_b32_e32 v9, v1
	v_mov_b32_e32 v10, v1
	v_mov_b32_e32 v11, v1
	v_mov_b32_e32 v12, v1
	v_mov_b32_e32 v13, v1
	v_mov_b64_e32 v[30:31], v[14:15]
	v_mov_b64_e32 v[46:47], v[14:15]
	v_mov_b64_e32 v[62:63], v[14:15]
	v_mov_b64_e32 v[78:79], v[14:15]
	v_mov_b64_e32 v[94:95], v[14:15]
	v_mov_b64_e32 v[110:111], v[14:15]
	v_mov_b64_e32 v[126:127], v[14:15]
	v_mov_b64_e32 v[142:143], v[14:15]
	s_mov_b32 s49, 2
	s_mov_b32 s53, 0
	v_cmp_lt_u32_e64 s[42:43], s66, v193
	s_mov_b64 s[20:21], 0
	v_mov_b32_e32 v202, 0
	v_mov_b64_e32 v[28:29], v[12:13]
	v_mov_b64_e32 v[26:27], v[10:11]
	v_mov_b64_e32 v[24:25], v[8:9]
	v_mov_b64_e32 v[22:23], v[6:7]
	v_mov_b64_e32 v[20:21], v[4:5]
	v_mov_b64_e32 v[18:19], v[2:3]
	v_mov_b64_e32 v[16:17], v[0:1]
	v_mov_b64_e32 v[44:45], v[12:13]
	v_mov_b64_e32 v[42:43], v[10:11]
	v_mov_b64_e32 v[40:41], v[8:9]
	v_mov_b64_e32 v[38:39], v[6:7]
	v_mov_b64_e32 v[36:37], v[4:5]
	v_mov_b64_e32 v[34:35], v[2:3]
	v_mov_b64_e32 v[32:33], v[0:1]
	v_mov_b64_e32 v[60:61], v[12:13]
	v_mov_b64_e32 v[58:59], v[10:11]
	v_mov_b64_e32 v[56:57], v[8:9]
	v_mov_b64_e32 v[54:55], v[6:7]
	v_mov_b64_e32 v[52:53], v[4:5]
	v_mov_b64_e32 v[50:51], v[2:3]
	v_mov_b64_e32 v[48:49], v[0:1]
	v_mov_b64_e32 v[76:77], v[12:13]
	v_mov_b64_e32 v[74:75], v[10:11]
	v_mov_b64_e32 v[72:73], v[8:9]
	v_mov_b64_e32 v[70:71], v[6:7]
	v_mov_b64_e32 v[68:69], v[4:5]
	v_mov_b64_e32 v[66:67], v[2:3]
	v_mov_b64_e32 v[64:65], v[0:1]
	v_mov_b64_e32 v[92:93], v[12:13]
	v_mov_b64_e32 v[90:91], v[10:11]
	v_mov_b64_e32 v[88:89], v[8:9]
	v_mov_b64_e32 v[86:87], v[6:7]
	v_mov_b64_e32 v[84:85], v[4:5]
	v_mov_b64_e32 v[82:83], v[2:3]
	v_mov_b64_e32 v[80:81], v[0:1]
	v_mov_b64_e32 v[108:109], v[12:13]
	v_mov_b64_e32 v[106:107], v[10:11]
	v_mov_b64_e32 v[104:105], v[8:9]
	v_mov_b64_e32 v[102:103], v[6:7]
	v_mov_b64_e32 v[100:101], v[4:5]
	v_mov_b64_e32 v[98:99], v[2:3]
	v_mov_b64_e32 v[96:97], v[0:1]
	v_mov_b64_e32 v[124:125], v[12:13]
	v_mov_b64_e32 v[122:123], v[10:11]
	v_mov_b64_e32 v[120:121], v[8:9]
	v_mov_b64_e32 v[118:119], v[6:7]
	v_mov_b64_e32 v[116:117], v[4:5]
	v_mov_b64_e32 v[114:115], v[2:3]
	v_mov_b64_e32 v[112:113], v[0:1]
	v_mov_b64_e32 v[140:141], v[12:13]
	v_mov_b64_e32 v[138:139], v[10:11]
	v_mov_b64_e32 v[136:137], v[8:9]
	v_mov_b64_e32 v[134:135], v[6:7]
	v_mov_b64_e32 v[132:133], v[4:5]
	v_mov_b64_e32 v[130:131], v[2:3]
	v_mov_b64_e32 v[128:129], v[0:1]
	s_waitcnt lgkmcnt(0)
	s_barrier
	s_branch .LBB0_598
	.p2align 8

.LBB0_645:
	s_ashr_i32 s20, s26, 3
	s_lshr_b32 s21, s20, 29
	s_add_i32 s21, s20, s21
	s_and_b32 s27, s26, 7
	s_ashr_i32 s23, s21, 3
	s_and_b32 s21, s21, -8
	v_mov_b32_e32 v12, v206
	s_mulk_i32 s27, 0x900
	s_sub_i32 s42, s20, s21
	s_add_i32 s40, s27, 0x100
	v_and_b32_e32 v13, 31, v12
	v_ashrrev_i32_e32 v0, 1, v12
	s_lshl_b32 s31, s42, 8
	v_and_b32_e32 v0, 0xffffffe0, v0
	v_or_b32_e32 v2, s40, v13
	s_lshl_b32 s22, s23, 7
	s_waitcnt vmcnt(20)
	v_add3_u32 v146, v2, v0, s31
	s_waitcnt lgkmcnt(0)
	v_mov_b64_e32 v[2:3], s[84:85]
	s_movk_i32 s4, 0xc00
	s_waitcnt vmcnt(17)
	v_bfe_u32 v156, v12, 5, 1
	s_lshl_b32 s20, s23, 6
	s_ashr_i32 s23, s22, 31
	v_mad_i64_i32 v[2:3], s[40:41], v146, s4, v[2:3]
	s_and_b32 s20, s20, 0xffffff80
	v_lshl_add_u64 v[2:3], s[22:23], 1, v[2:3]
	v_lshlrev_b32_e32 v0, 4, v156
	s_ashr_i32 s21, s20, 31
	v_lshl_add_u64 v[2:3], v[2:3], 0, v[0:1]
	v_ashrrev_i32_e32 v0, 31, v12
	s_mul_hi_i32 s29, s20, 0x9000
	s_mul_i32 s28, s20, 0x9000
	s_lshl_b64 s[20:21], s[20:21], 1
	v_lshrrev_b32_e32 v0, 28, v0
	s_add_u32 s20, s84, s20
	v_add_u32_e32 v14, v12, v0
	s_addc_u32 s21, s85, s21
	v_ashrrev_i32_e32 v157, 4, v14
	v_add_u32_e32 v0, s27, v157
	v_mov_b64_e32 v[4:5], s[20:21]
	v_mad_i64_i32 v[6:7], s[40:41], v0, s4, v[4:5]
	v_lshlrev_b32_e32 v0, 7, v157
	v_lshlrev_b32_e32 v8, 3, v12
	v_add_u32_e32 v15, 0x200, v12
	v_sub_u32_e32 v8, v8, v0
	v_ashrrev_i32_e32 v0, 31, v15
	v_lshrrev_b32_e32 v0, 28, v0
	v_ashrrev_i32_e32 v9, 31, v8
	v_add_u32_e32 v16, v15, v0
	v_lshlrev_b64 v[8:9], 1, v[8:9]
	v_ashrrev_i32_e32 v158, 4, v16
	v_lshl_add_u64 v[6:7], v[6:7], 0, v[8:9]
	v_add_u32_e32 v0, s27, v158
	global_load_dwordx4 v[98:101], v[6:7], off offset:2048
	v_mad_i64_i32 v[4:5], s[40:41], v0, s4, v[4:5]
	v_lshlrev_b32_e32 v0, 7, v158
	v_lshlrev_b32_e32 v6, 3, v15
	v_sub_u32_e32 v6, v6, v0
	v_ashrrev_i32_e32 v7, 31, v6
	s_add_u32 s28, s86, s28
	v_lshlrev_b64 v[6:7], 1, v[6:7]
	s_addc_u32 s29, s87, s29
	v_lshl_add_u64 v[4:5], v[4:5], 0, v[6:7]
	global_load_dwordx4 v[102:105], v[4:5], off offset:2048
	v_ashrrev_i32_e32 v17, 3, v12
	v_mov_b64_e32 v[4:5], s[28:29]
	s_mov_b32 s4, 0x9000
	s_lshl_b32 s30, s27, 1
	v_mad_i64_i32 v[10:11], s[28:29], v17, s4, v[4:5]
	s_mov_b32 s31, s52
	v_lshlrev_b32_e32 v0, 4, v12
	v_lshl_add_u64 v[10:11], v[10:11], 0, s[30:31]
	v_and_b32_e32 v0, 0x70, v0
	v_lshl_add_u64 v[148:149], v[10:11], 0, v[0:1]
	v_ashrrev_i32_e32 v10, 3, v15
	v_mad_i64_i32 v[4:5], s[28:29], v10, s4, v[4:5]
	v_lshl_add_u64 v[4:5], v[4:5], 0, s[30:31]
	v_lshl_add_u64 v[150:151], v[4:5], 0, v[0:1]
	global_load_dwordx4 v[138:141], v[148:149], off
	global_load_dwordx4 v[142:145], v[150:151], off
	global_load_dwordx4 v[106:109], v[2:3], off
	global_load_dwordx4 v[110:113], v[2:3], off offset:32
	global_load_dwordx4 v[114:117], v[2:3], off offset:64
	global_load_dwordx4 v[118:121], v[2:3], off offset:96
	global_load_dwordx4 v[122:125], v[2:3], off offset:128
	global_load_dwordx4 v[126:129], v[2:3], off offset:160
	global_load_dwordx4 v[130:133], v[2:3], off offset:192
	global_load_dwordx4 v[134:137], v[2:3], off offset:224
	v_and_b32_e32 v5, 0xffffff0, v14
	v_sub_u32_e32 v5, v12, v5
	v_lshlrev_b32_e32 v11, 8, v157
	v_bitop3_b32 v5, v5, v157, 15 bitop3:0x78
	v_lshl_add_u32 v159, v5, 4, v11
	v_and_b32_e32 v5, 0xffffff0, v16
	v_sub_u32_e32 v5, v15, v5
	v_lshlrev_b32_e32 v11, 8, v158
	v_bitop3_b32 v5, v5, v158, 15 bitop3:0x78
	s_waitcnt vmcnt(28)
	v_lshl_add_u32 v160, v5, 4, v11
	v_lshrrev_b32_e32 v11, 1, v17
	v_xor_b32_e32 v11, v11, v12
	v_lshlrev_b32_e32 v5, 7, v17
	v_lshlrev_b32_e32 v11, 4, v11
	s_movk_i32 s4, 0x70
	v_and_or_b32 v161, v11, s4, v5
	v_lshlrev_b32_e32 v5, 7, v10
	v_lshrrev_b32_e32 v10, 1, v10
	v_and_b32_e32 v2, 3, v12
	v_lshlrev_b32_e32 v3, 1, v12
	v_xor_b32_e32 v10, v10, v12
	v_and_or_b32 v2, v3, 8, v2
	v_lshrrev_b32_e32 v3, 1, v12
	v_lshlrev_b32_e32 v10, 4, v10
	v_and_b32_e32 v3, 4, v3
	v_and_or_b32 v162, v10, s4, v5
	v_mov_b32_e32 v5, 0x6000
	v_lshl_or_b32 v164, v13, 7, v5
	v_bitop3_b32 v5, v2, v156, v3 bitop3:0x36
	v_lshlrev_b32_e32 v165, 4, v5
	v_or_b32_e32 v5, 2, v156
	v_bitop3_b32 v5, v2, v5, v3 bitop3:0x36
	v_lshlrev_b32_e32 v166, 4, v5
	v_or_b32_e32 v5, 4, v156
	v_bitop3_b32 v5, v2, v5, v3 bitop3:0x36
	v_lshlrev_b32_e32 v167, 4, v5
	v_or_b32_e32 v5, 6, v156
	v_bitop3_b32 v5, v2, v5, v3 bitop3:0x36
	v_lshlrev_b32_e32 v168, 4, v5
	v_or_b32_e32 v5, 8, v156
	v_or_b32_e32 v4, v2, v3
	v_bitop3_b32 v5, v2, v5, v3 bitop3:0x36
	v_and_or_b32 v4, v12, 16, v4
	v_lshlrev_b32_e32 v169, 4, v5
	v_or_b32_e32 v5, 10, v156
	v_lshrrev_b32_e32 v0, 5, v12
	v_lshlrev_b32_e32 v163, 8, v4
	v_bfe_u32 v4, v12, 1, 3
	v_bitop3_b32 v5, v2, v5, v3 bitop3:0x36
	v_lshlrev_b32_e32 v170, 4, v5
	v_or_b32_e32 v5, 12, v156
	v_bitop3_b32 v0, v0, v4, 1 bitop3:0x6c
	v_bitop3_b32 v5, v2, v5, v3 bitop3:0x36
	v_lshlrev_b32_e32 v173, 4, v0
	v_bitop3_b32 v0, v156, v4, 2 bitop3:0x36
	v_lshlrev_b32_e32 v171, 4, v5
	v_or_b32_e32 v5, 14, v156
	v_lshlrev_b32_e32 v174, 4, v0
	v_bitop3_b32 v0, v156, v4, 4 bitop3:0x36
	v_bitop3_b32 v2, v2, v5, v3 bitop3:0x36
	v_lshlrev_b32_e32 v175, 4, v0
	v_bitop3_b32 v0, v156, v4, 6 bitop3:0x36
	v_mov_b32_e32 v14, v1
	v_mov_b32_e32 v15, v1
	v_lshl_add_u64 v[152:153], s[20:21], 0, v[8:9]
	v_lshl_add_u64 v[154:155], s[20:21], 0, v[6:7]
	v_lshlrev_b32_e32 v172, 4, v2
	v_lshlrev_b32_e32 v176, 4, v0
	v_mov_b32_e32 v0, v1
	v_mov_b32_e32 v2, v1
	v_mov_b32_e32 v3, v1
	v_mov_b32_e32 v4, v1
	v_mov_b32_e32 v5, v1
	v_mov_b32_e32 v6, v1
	v_mov_b32_e32 v7, v1
	v_mov_b32_e32 v8, v1
	v_mov_b32_e32 v9, v1
	v_mov_b32_e32 v10, v1
	v_mov_b32_e32 v11, v1
	v_mov_b32_e32 v12, v1
	v_mov_b32_e32 v13, v1
	v_mov_b64_e32 v[64:65], v[14:15]
	v_mov_b64_e32 v[48:49], v[14:15]
	v_mov_b64_e32 v[32:33], v[14:15]
	s_cmp_lt_i32 s42, 0
	v_mov_b64_e32 v[62:63], v[12:13]
	v_mov_b64_e32 v[60:61], v[10:11]
	v_mov_b64_e32 v[58:59], v[8:9]
	v_mov_b64_e32 v[56:57], v[6:7]
	v_mov_b64_e32 v[54:55], v[4:5]
	v_mov_b64_e32 v[52:53], v[2:3]
	v_mov_b64_e32 v[50:51], v[0:1]
	v_mov_b64_e32 v[46:47], v[12:13]
	v_mov_b64_e32 v[44:45], v[10:11]
	v_mov_b64_e32 v[42:43], v[8:9]
	v_mov_b64_e32 v[40:41], v[6:7]
	v_mov_b64_e32 v[38:39], v[4:5]
	v_mov_b64_e32 v[36:37], v[2:3]
	v_mov_b64_e32 v[34:35], v[0:1]
	v_mov_b64_e32 v[30:31], v[12:13]
	v_mov_b64_e32 v[28:29], v[10:11]
	v_mov_b64_e32 v[26:27], v[8:9]
	v_mov_b64_e32 v[24:25], v[6:7]
	v_mov_b64_e32 v[22:23], v[4:5]
	v_mov_b64_e32 v[20:21], v[2:3]
	v_mov_b64_e32 v[18:19], v[0:1]
	v_mov_b64_e32 v[16:17], v[14:15]
	s_mov_b32 s31, 0
	v_ashrrev_i32_e32 v147, 31, v146
	s_cselect_b32 s28, 4, 36
	s_cselect_b32 s29, -3, 1
	v_mov_b32_e32 v177, 0
	v_mov_b32_e32 v179, 0xf149f2ca
	v_mov_b64_e32 v[14:15], v[12:13]
	v_mov_b64_e32 v[12:13], v[10:11]
	v_mov_b64_e32 v[10:11], v[8:9]
	v_mov_b64_e32 v[8:9], v[6:7]
	v_mov_b64_e32 v[6:7], v[4:5]
	v_mov_b64_e32 v[4:5], v[2:3]
	v_mov_b64_e32 v[2:3], v[0:1]
	s_waitcnt vmcnt(11)
	ds_write_b128 v159, v[98:101]
	s_waitcnt vmcnt(10)
	ds_write_b128 v160, v[102:105]
	s_waitcnt vmcnt(9)
	ds_write_b128 v161, v[138:141] offset:24576
	s_waitcnt vmcnt(8)
	ds_write_b128 v162, v[142:145] offset:24576
	s_waitcnt vmcnt(0)
	s_waitcnt lgkmcnt(0)
	s_barrier
	.p2align 8

.LBB0_671:
	s_or_b64 exec, exec, s[22:23]
	s_load_dwordx16 s[4:19], s[0:1], 0xa8
	s_mul_i32 s22, s28, 0x9000
	s_mul_hi_i32 s23, s28, 0x9000
	global_load_dwordx4 v[152:155], v[24:25], off
	v_ashrrev_i32_e32 v9, 3, v4
	s_waitcnt lgkmcnt(0)
	s_add_u32 s22, s14, s22
	s_addc_u32 s23, s15, s23
	v_mov_b64_e32 v[24:25], s[22:23]
	s_mov_b32 s4, 0x9000
	s_lshl_b32 s44, s27, 1
	v_mad_i64_i32 v[26:27], s[22:23], v9, s4, v[24:25]
	s_mov_b32 s45, s52
	v_lshlrev_b32_e32 v0, 4, v4
	v_ashrrev_i32_e32 v15, 3, v18
	v_lshl_add_u64 v[26:27], v[26:27], 0, s[44:45]
	v_and_b32_e32 v0, 0x70, v0
	v_mad_i64_i32 v[18:19], s[22:23], v15, s4, v[24:25]
	v_lshl_add_u64 v[166:167], v[26:27], 0, v[0:1]
	v_lshl_add_u64 v[18:19], v[18:19], 0, s[44:45]
	v_lshl_add_u64 v[168:169], v[18:19], 0, v[0:1]
	global_load_dwordx4 v[156:159], v[166:167], off
	global_load_dwordx4 v[160:163], v[168:169], off
	v_lshlrev_b32_e32 v21, 1, v4
	v_lshrrev_b32_e32 v24, 1, v4
	s_movk_i32 s4, 0x180
	v_lshrrev_b32_e32 v26, 1, v175
	v_mov_b32_e32 v3, 0x6000
	v_and_b32_e32 v0, 3, v4
	v_mul_lo_u32 v25, v175, s4
	v_lshrrev_b32_e32 v30, 1, v183
	v_lshl_or_b32 v184, v5, 7, v3
	v_lshl_add_u64 v[18:19], v[22:23], 1, s[20:21]
	v_and_b32_e32 v5, 8, v21
	v_and_b32_e32 v21, 4, v24
	v_bitop3_b32 v8, v26, v8, 7 bitop3:0x6c
	v_lshlrev_b32_e32 v22, 7, v9
	v_lshrrev_b32_e32 v9, 1, v9
	v_lshlrev_b32_e32 v23, 7, v15
	v_lshrrev_b32_e32 v15, 1, v15
	v_lshrrev_b32_e32 v28, 1, v179
	v_mul_lo_u32 v29, v183, s4
	v_bitop3_b32 v20, v30, v20, 7 bitop3:0x6c
	v_or3_b32 v0, v5, v0, v21
	v_lshl_add_u32 v185, v8, 4, v25
	v_xor_b32_e32 v5, v9, v4
	v_xor_b32_e32 v8, v15, v4
	v_mul_lo_u32 v27, v179, s4
	v_bitop3_b32 v14, v28, v14, 7 bitop3:0x6c
	v_lshl_add_u32 v187, v20, 4, v29
	v_lshlrev_b32_e32 v5, 4, v5
	v_lshlrev_b32_e32 v8, 4, v8
	s_movk_i32 s5, 0x70
	v_lshl_add_u32 v186, v14, 4, v27
	s_waitcnt vmcnt(4)
	ds_write_b128 v185, v[144:147]
	s_waitcnt vmcnt(3)
	ds_write_b128 v186, v[148:151]
	v_and_or_b32 v191, v5, s5, v22
	v_and_or_b32 v192, v8, s5, v23
	v_lshrrev_b32_e32 v9, 1, v0
	v_bfe_u32 v31, v4, 1, 3
	v_mov_b32_e32 v3, v1
	v_mov_b32_e32 v7, v1
	v_and_or_b32 v0, v4, 16, v0
	v_xor_b32_e32 v4, v9, v171
	v_bitop3_b32 v5, v9, v171, 2 bitop3:0x1e
	v_mov_b32_e32 v14, 0x3000
	v_lshl_add_u64 v[12:13], v[12:13], 1, s[20:21]
	v_lshl_add_u64 v[16:17], v[16:17], 1, s[20:21]
	v_bitop3_b32 v24, v171, v24, 7 bitop3:0x78
	v_bitop3_b32 v26, v171, v31, 2 bitop3:0x36
	v_bitop3_b32 v28, v171, v31, 4 bitop3:0x36
	v_bitop3_b32 v30, v171, v31, 6 bitop3:0x36
	v_bitop3_b32 v8, v9, v171, 4 bitop3:0x1e
	v_bitop3_b32 v9, v9, v171, 6 bitop3:0x1e
	v_mad_u32_u24 v194, v0, s4, v14
	v_lshlrev_b32_e32 v195, 4, v4
	v_lshlrev_b32_e32 v196, 4, v5
	v_mov_b32_e32 v14, v1
	v_mov_b32_e32 v15, v1
	v_lshlrev_b32_e32 v188, 4, v24
	v_lshlrev_b32_e32 v189, 4, v26
	v_lshlrev_b32_e32 v190, 4, v28
	s_cmp_lt_i32 s30, 1
	v_mul_u32_u24_e32 v193, 0x180, v0
	v_lshlrev_b32_e32 v197, 4, v8
	v_lshlrev_b32_e32 v198, 4, v9
	v_lshlrev_b32_e32 v199, 4, v30
	v_mov_b32_e32 v0, v1
	v_mov_b32_e32 v8, v1
	v_mov_b32_e32 v9, v1
	v_ashrrev_i32_e32 v165, 31, v164
	s_cselect_b32 s20, 4, 36
	s_waitcnt vmcnt(2)
	ds_write_b128 v187, v[152:155]
	s_waitcnt vmcnt(1)
	ds_write_b128 v191, v[156:159] offset:24576
	s_waitcnt vmcnt(0)
	ds_write_b128 v192, v[160:163] offset:24576
	s_waitcnt lgkmcnt(0)
	s_barrier
	s_load_dwordx4 s[44:47], s[0:1], 0xe8
	s_cselect_b32 s21, -3, 1
	v_cndmask_b32_e64 v170, 11, 7, vcc
	s_mov_b32 s31, 0
	v_cndmask_b32_e64 v174, 11, 7, s[40:41]
	s_waitcnt lgkmcnt(0)
	v_lshl_add_u64 v[2:3], v[2:3], 1, s[44:45]
	v_lshl_add_u64 v[4:5], v[6:7], 1, s[44:45]
	v_lshl_add_u64 v[6:7], v[10:11], 1, s[44:45]
	v_cndmask_b32_e32 v173, v13, v3, vcc
	v_cndmask_b32_e32 v172, v12, v2, vcc
	v_cndmask_b32_e64 v177, v17, v5, s[40:41]
	v_cndmask_b32_e64 v176, v16, v4, s[40:41]
	v_cndmask_b32_e64 v181, v19, v7, s[42:43]
	v_cndmask_b32_e64 v180, v18, v6, s[42:43]
	v_mov_b32_e32 v2, v1
	v_mov_b32_e32 v3, v1
	v_mov_b32_e32 v4, v1
	v_mov_b32_e32 v5, v1
	v_mov_b32_e32 v6, v1
	v_mov_b32_e32 v7, v1
	v_mov_b32_e32 v10, v1
	v_mov_b32_e32 v11, v1
	v_mov_b32_e32 v12, v1
	v_mov_b32_e32 v13, v1
	v_mov_b64_e32 v[30:31], v[14:15]
	v_mov_b64_e32 v[46:47], v[14:15]
	v_mov_b64_e32 v[62:63], v[14:15]
	v_mov_b64_e32 v[78:79], v[14:15]
	v_cndmask_b32_e64 v178, 11, 7, s[42:43]
	v_mov_b32_e32 v200, 0
	v_mov_b32_e32 v203, 0xf149f2ca
	v_mov_b64_e32 v[28:29], v[12:13]
	v_mov_b64_e32 v[26:27], v[10:11]
	v_mov_b64_e32 v[24:25], v[8:9]
	v_mov_b64_e32 v[22:23], v[6:7]
	v_mov_b64_e32 v[20:21], v[4:5]
	v_mov_b64_e32 v[18:19], v[2:3]
	v_mov_b64_e32 v[16:17], v[0:1]
	v_mov_b64_e32 v[44:45], v[12:13]
	v_mov_b64_e32 v[42:43], v[10:11]
	v_mov_b64_e32 v[40:41], v[8:9]
	v_mov_b64_e32 v[38:39], v[6:7]
	v_mov_b64_e32 v[36:37], v[4:5]
	v_mov_b64_e32 v[34:35], v[2:3]
	v_mov_b64_e32 v[32:33], v[0:1]
	v_mov_b64_e32 v[60:61], v[12:13]
	v_mov_b64_e32 v[58:59], v[10:11]
	v_mov_b64_e32 v[56:57], v[8:9]
	v_mov_b64_e32 v[54:55], v[6:7]
	v_mov_b64_e32 v[52:53], v[4:5]
	v_mov_b64_e32 v[50:51], v[2:3]
	v_mov_b64_e32 v[48:49], v[0:1]
	v_mov_b64_e32 v[76:77], v[12:13]
	v_mov_b64_e32 v[74:75], v[10:11]
	v_mov_b64_e32 v[72:73], v[8:9]
	v_mov_b64_e32 v[70:71], v[6:7]
	v_mov_b64_e32 v[68:69], v[4:5]
	v_mov_b64_e32 v[66:67], v[2:3]
	v_mov_b64_e32 v[64:65], v[0:1]
	.p2align 8

.LBB0_690:
	s_load_dwordx16 s[4:19], s[0:1], 0xa8
	s_and_b32 s20, s22, 7
	s_mul_i32 s29, s20, 0x900
	v_and_b32_e32 v5, 31, v4
	s_add_i32 s40, s27, s29
	v_ashrrev_i32_e32 v0, 1, v4
	v_and_b32_e32 v6, 0xffffffe0, v0
	v_or_b32_e32 v0, s40, v5
	s_lshl_b32 s42, s28, 6
	v_add_u32_e32 v90, v0, v6
	s_waitcnt lgkmcnt(0)
	v_mov_b64_e32 v[2:3], s[12:13]
	s_movk_i32 s4, 0xa00
	v_bfe_u32 v96, v4, 5, 1
	s_lshl_b32 s20, s28, 4
	v_mad_i64_i32 v[2:3], s[40:41], v90, s4, v[2:3]
	s_ashr_i32 s43, s42, 31
	s_andn2_b32 s20, s20, 63
	v_lshl_add_u64 v[2:3], s[42:43], 1, v[2:3]
	v_lshlrev_b32_e32 v0, 4, v96
	s_ashr_i32 s21, s20, 31
	v_lshl_add_u64 v[2:3], v[2:3], 0, v[0:1]
	v_ashrrev_i32_e32 v0, 31, v4
	s_sub_i32 s26, s26, s23
	s_mul_hi_i32 s44, s20, 0x9000
	s_mul_i32 s45, s20, 0x9000
	s_lshl_b64 s[20:21], s[20:21], 1
	v_lshrrev_b32_e32 v0, 29, v0
	s_add_u32 s20, s12, s20
	v_add_u32_e32 v7, v4, v0
	s_addc_u32 s21, s13, s21
	v_ashrrev_i32_e32 v10, 3, v7
	global_load_dwordx4 v[66:69], v[2:3], off
	global_load_dwordx4 v[70:73], v[2:3], off offset:32
	global_load_dwordx4 v[74:77], v[2:3], off offset:64
	global_load_dwordx4 v[78:81], v[2:3], off offset:96
	s_add_u32 s40, s14, s45
	v_add_u32_e32 v91, s29, v10
	v_mov_b64_e32 v[2:3], s[20:21]
	s_addc_u32 s41, s15, s44
	v_mad_i64_i32 v[8:9], s[44:45], v91, s4, v[2:3]
	v_lshlrev_b32_e32 v0, 6, v10
	v_lshlrev_b32_e32 v2, 3, v4
	v_sub_u32_e32 v2, v2, v0
	v_ashrrev_i32_e32 v3, 31, v2
	v_lshl_add_u64 v[8:9], v[2:3], 1, v[8:9]
	global_load_dwordx4 v[82:85], v[8:9], off offset:2048
	v_ashrrev_i32_e32 v11, 3, v4
	v_mov_b64_e32 v[8:9], s[40:41]
	s_mov_b32 s4, 0x9000
	v_mad_i64_i32 v[8:9], s[40:41], v11, s4, v[8:9]
	s_lshl_b32 s40, s29, 1
	s_mov_b32 s41, s52
	v_lshlrev_b32_e32 v0, 4, v4
	v_lshl_add_u64 v[8:9], v[8:9], 0, s[40:41]
	v_and_b32_e32 v0, 0x70, v0
	v_lshl_add_u64 v[92:93], v[8:9], 0, v[0:1]
	global_load_dwordx4 v[86:89], v[92:93], off
	v_and_b32_e32 v0, 0xffffff8, v7
	v_sub_u32_e32 v0, v4, v0
	v_lshrrev_b32_e32 v8, 1, v10
	v_lshlrev_b32_e32 v7, 7, v10
	v_bitop3_b32 v0, v8, v0, 7 bitop3:0x6c
	v_lshl_add_u32 v97, v0, 4, v7
	v_lshrrev_b32_e32 v7, 1, v11
	v_xor_b32_e32 v7, v7, v4
	v_lshlrev_b32_e32 v0, 7, v11
	v_lshlrev_b32_e32 v7, 4, v7
	s_movk_i32 s4, 0x70
	s_movk_i32 s5, 0xa00
	v_and_or_b32 v98, v7, s4, v0
	s_cmp_lt_i32 s26, -3
	s_waitcnt vmcnt(1)
	ds_write_b128 v97, v[82:85]
	s_waitcnt vmcnt(0)
	ds_write_b128 v98, v[86:89] offset:24576
	s_waitcnt lgkmcnt(0)
	s_barrier
	s_cbranch_scc1 .LBB0_702
	v_lshl_add_u64 v[94:95], v[2:3], 1, s[20:21]
	v_lshlrev_b32_e32 v0, 1, v4
	v_lshrrev_b32_e32 v3, 1, v4
	v_and_b32_e32 v0, 8, v0
	v_and_b32_e32 v2, 3, v4
	v_and_b32_e32 v7, 4, v3
	v_or3_b32 v0, v0, v2, v7
	v_and_or_b32 v2, v4, 16, v0
	v_lshlrev_b32_e32 v99, 7, v2
	v_or_b32_e32 v2, s27, v5
	v_lshrrev_b32_e32 v0, 1, v0
	v_add_u32_e32 v101, v2, v6
	v_bfe_u32 v2, v4, 1, 3
	v_mov_b32_e32 v4, 0x6000
	v_lshl_or_b32 v102, v5, 7, v4
	v_xor_b32_e32 v4, v0, v96
	v_lshlrev_b32_e32 v103, 4, v4
	v_bitop3_b32 v4, v0, v96, 2 bitop3:0x1e
	v_lshlrev_b32_e32 v104, 4, v4
	v_bitop3_b32 v4, v0, v96, 4 bitop3:0x1e
	v_bitop3_b32 v0, v0, v96, 6 bitop3:0x1e
	v_lshlrev_b32_e32 v106, 4, v0
	v_bitop3_b32 v0, v96, v3, 7 bitop3:0x78
	v_lshlrev_b32_e32 v114, 4, v0
	v_bitop3_b32 v0, v96, v2, 2 bitop3:0x36
	v_lshlrev_b32_e32 v115, 4, v0
	v_bitop3_b32 v0, v96, v2, 4 bitop3:0x36
	v_lshlrev_b32_e32 v116, 4, v0
	v_bitop3_b32 v0, v96, v2, 6 bitop3:0x36
	v_mov_b32_e32 v14, v1
	v_mov_b32_e32 v15, v1
	v_lshlrev_b32_e32 v105, 4, v4
	v_lshlrev_b32_e32 v117, 4, v0
	v_mov_b32_e32 v0, v1
	v_mov_b32_e32 v2, v1
	v_mov_b32_e32 v3, v1
	v_mov_b32_e32 v4, v1
	v_mov_b32_e32 v5, v1
	v_mov_b32_e32 v6, v1
	v_mov_b32_e32 v7, v1
	v_mov_b32_e32 v8, v1
	v_mov_b32_e32 v9, v1
	v_mov_b32_e32 v10, v1
	v_mov_b32_e32 v11, v1
	v_mov_b32_e32 v12, v1
	v_mov_b32_e32 v13, v1
	v_mov_b64_e32 v[32:33], v[14:15]
	v_mov_b64_e32 v[30:31], v[12:13]
	v_mov_b64_e32 v[28:29], v[10:11]
	v_mov_b64_e32 v[26:27], v[8:9]
	v_mov_b64_e32 v[24:25], v[6:7]
	v_mov_b64_e32 v[22:23], v[4:5]
	v_mov_b64_e32 v[20:21], v[2:3]
	v_mov_b64_e32 v[18:19], v[0:1]
	v_mov_b64_e32 v[16:17], v[14:15]
	v_mul_i32_i24_e32 v100, -8, v96
	s_add_i32 s27, s26, 3
	v_add_u32_e32 v107, -1, v101
	v_add_u32_e32 v108, -2, v101
	v_add_u32_e32 v109, -3, v101
	s_mov_b32 s29, -4
	v_add_u32_e32 v110, -4, v101
	v_add_u32_e32 v111, -5, v101
	v_add_u32_e32 v112, -6, v101
	v_add_u32_e32 v113, -7, v101
	v_mov_b32_e32 v118, 0
	v_mov_b32_e32 v119, 0xf149f2ca
	v_mov_b64_e32 v[14:15], v[12:13]
	v_mov_b64_e32 v[12:13], v[10:11]
	v_mov_b64_e32 v[10:11], v[8:9]
	v_mov_b64_e32 v[8:9], v[6:7]
	v_mov_b64_e32 v[6:7], v[4:5]
	v_mov_b64_e32 v[4:5], v[2:3]
	v_mov_b64_e32 v[2:3], v[0:1]
	.p2align 8

.LBB0_712:
	s_cmp_lt_u32 s21, s62
	s_cselect_b64 s[26:27], -1, 0
	s_cmp_ge_u32 s21, s62
	s_cselect_b64 s[58:59], -1, 0
	s_abs_i32 s40, s20
	v_cvt_f32_u32_e32 v0, s40
	s_sub_i32 s41, s21, s62
	s_min_u32 s21, s21, s41
	s_sub_i32 s41, 0, s40
	v_rcp_iflag_f32_e32 v0, v0
	v_readlane_b32 s4, v254, 46
	s_add_i32 s42, s21, s4
	s_xor_b32 s43, s21, s20
	v_mul_f32_e32 v0, 0x4f7ffffe, v0
	v_cvt_u32_f32_e32 v0, v0
	s_abs_i32 s21, s21
	s_ashr_i32 s43, s43, 31
	s_load_dwordx16 s[4:19], s[0:1], 0xa8
	v_readfirstlane_b32 s44, v0
	s_mul_i32 s41, s41, s44
	s_mul_hi_u32 s41, s44, s41
	s_add_i32 s44, s44, s41
	s_mul_hi_u32 s41, s21, s44
	s_mul_i32 s44, s41, s40
	s_sub_i32 s21, s21, s44
	s_add_i32 s44, s41, 1
	s_sub_i32 s45, s21, s40
	s_cmp_ge_u32 s21, s40
	s_cselect_b32 s41, s44, s41
	s_cselect_b32 s21, s45, s21
	s_add_i32 s44, s41, 1
	s_cmp_ge_u32 s21, s40
	s_cselect_b32 s21, s44, s41
	s_xor_b32 s21, s21, s43
	s_sub_i32 s65, s21, s43
	s_mul_i32 s20, s65, s20
	s_sub_i32 s20, s42, s20
	s_lshl_b32 s54, s20, 8
	s_lshl_b32 s56, s65, 8
	s_and_b64 s[20:21], s[26:27], exec
	s_cselect_b32 s40, 0, s53
	s_ashr_i32 s55, s54, 31
	s_lshl_b64 s[20:21], s[54:55], 11
	s_waitcnt lgkmcnt(0)
	s_add_u32 s41, s10, s20
	s_addc_u32 s42, s11, s21
	s_add_i32 s20, s56, s40
	s_ashr_i32 s21, s20, 31
	s_lshl_b64 s[20:21], s[20:21], 11
	v_mov_b32_e32 v193, v206
	s_add_u32 s40, s46, s20
	s_addc_u32 s43, s47, s21
	v_lshlrev_b32_e32 v0, 4, v193
	v_ashrrev_i32_e32 v40, 3, v193
	v_and_b32_e32 v0, 0x70, v0
	s_and_b64 s[20:21], s[26:27], exec
	v_lshl_or_b32 v0, v40, 11, v0
	s_cselect_b32 s21, s42, s43
	s_cselect_b32 s20, s41, s40
	v_add_u32_e32 v34, 0x20000, v0
	v_add_u32_e32 v36, 0x40000, v0
	s_cselect_b32 s49, s43, s42
	s_cselect_b32 s48, s40, s41
	global_load_dwordx4 v[2:5], v0, s[20:21]
	global_load_dwordx4 v[6:9], v0, s[48:49]
	global_load_dwordx4 v[10:13], v34, s[20:21]
	global_load_dwordx4 v[14:17], v34, s[48:49]
	global_load_dwordx4 v[18:21], v36, s[20:21]
	global_load_dwordx4 v[22:25], v36, s[48:49]
	v_add_u32_e32 v38, 0x60000, v0
	global_load_dwordx4 v[26:29], v38, s[20:21]
	global_load_dwordx4 v[30:33], v38, s[48:49]
	global_load_dwordx4 v[144:147], v0, s[20:21] offset:128
	global_load_dwordx4 v[148:151], v0, s[48:49] offset:128
	global_load_dwordx4 v[152:155], v34, s[20:21] offset:128
	global_load_dwordx4 v[156:159], v34, s[48:49] offset:128
	global_load_dwordx4 v[160:163], v36, s[20:21] offset:128
	global_load_dwordx4 v[164:167], v36, s[48:49] offset:128
	global_load_dwordx4 v[168:171], v38, s[20:21] offset:128
	global_load_dwordx4 v[172:175], v38, s[48:49] offset:128
	v_lshlrev_b32_e32 v48, 7, v40
	v_lshrrev_b32_e32 v40, 1, v40
	s_movk_i32 s4, 0x100
	v_xor_b32_e32 v40, v40, v193
	s_add_u32 s48, s48, 0x100
	v_cmp_gt_u32_e32 vcc, s4, v193
	v_lshlrev_b32_e32 v40, 4, v40
	s_movk_i32 s4, 0x70
	s_addc_u32 s49, s49, 0
	v_lshlrev_b32_e32 v42, 7, v193
	v_bfe_u32 v43, v193, 1, 3
	v_lshrrev_b32_e32 v192, 5, v193
	v_bfe_u32 v194, v193, 5, 1
	v_and_or_b32 v201, v40, s4, v48
	s_add_u32 s20, s20, 0x100
	v_mov_b32_e32 v35, v1
	v_mov_b32_e32 v37, v1
	v_mov_b32_e32 v39, v1
	v_ashrrev_i32_e32 v41, 8, v193
	v_and_b32_e32 v44, 0xf80, v42
	v_and_b32_e32 v42, 0x6f80, v42
	v_bitop3_b32 v45, v192, v43, 1 bitop3:0x6c
	v_bitop3_b32 v46, v194, v43, 2 bitop3:0x36
	v_bitop3_b32 v47, v194, v43, 4 bitop3:0x36
	v_bitop3_b32 v43, v194, v43, 6 bitop3:0x36
	s_addc_u32 s21, s21, 0
	v_cmp_eq_u32_e64 s[40:41], 1, v41
	v_cmp_ne_u32_e64 s[44:45], 1, v41
	v_lshl_or_b32 v195, v41, 14, v44
	v_or_b32_e32 v196, 0x8000, v42
	v_lshlrev_b32_e32 v197, 4, v45
	v_lshlrev_b32_e32 v198, 4, v46
	v_lshlrev_b32_e32 v199, 4, v47
	v_lshlrev_b32_e32 v200, 4, v43
	v_lshl_add_u64 v[176:177], s[48:49], 0, v[38:39]
	v_lshl_add_u64 v[178:179], s[48:49], 0, v[36:37]
	v_lshl_add_u64 v[180:181], s[48:49], 0, v[34:35]
	v_lshl_add_u64 v[182:183], s[48:49], 0, v[0:1]
	v_lshl_add_u64 v[184:185], s[20:21], 0, v[38:39]
	v_lshl_add_u64 v[186:187], s[20:21], 0, v[36:37]
	v_lshl_add_u64 v[188:189], s[20:21], 0, v[34:35]
	v_lshl_add_u64 v[190:191], s[20:21], 0, v[0:1]
	v_mov_b32_e32 v0, v1
	s_mov_b32 s26, 0
	v_cmp_lt_u32_e64 s[42:43], s66, v193
	s_mov_b32 s27, 0
	s_waitcnt vmcnt(15)
	ds_write_b128 v201, v[2:5]
	s_waitcnt vmcnt(14)
	ds_write_b128 v201, v[6:9] offset:32768
	s_waitcnt vmcnt(13)
	ds_write_b128 v201, v[10:13] offset:8192
	s_waitcnt vmcnt(12)
	ds_write_b128 v201, v[14:17] offset:40960
	s_waitcnt vmcnt(11)
	ds_write_b128 v201, v[18:21] offset:16384
	s_waitcnt vmcnt(10)
	ds_write_b128 v201, v[22:25] offset:49152
	s_waitcnt vmcnt(9)
	ds_write_b128 v201, v[26:29] offset:24576
	s_waitcnt vmcnt(8)
	ds_write_b128 v201, v[30:33] offset:57344
	v_mov_b32_e32 v14, v1
	v_mov_b32_e32 v15, v1
	v_mov_b32_e32 v2, v1
	v_mov_b32_e32 v3, v1
	v_mov_b32_e32 v4, v1
	v_mov_b32_e32 v5, v1
	v_mov_b32_e32 v6, v1
	v_mov_b32_e32 v7, v1
	v_mov_b32_e32 v8, v1
	v_mov_b32_e32 v9, v1
	v_mov_b32_e32 v10, v1
	v_mov_b32_e32 v11, v1
	v_mov_b32_e32 v12, v1
	v_mov_b32_e32 v13, v1
	v_mov_b64_e32 v[30:31], v[14:15]
	v_mov_b64_e32 v[46:47], v[14:15]
	v_mov_b64_e32 v[62:63], v[14:15]
	v_mov_b64_e32 v[78:79], v[14:15]
	v_mov_b64_e32 v[94:95], v[14:15]
	v_mov_b64_e32 v[110:111], v[14:15]
	v_mov_b64_e32 v[126:127], v[14:15]
	v_mov_b64_e32 v[142:143], v[14:15]
	v_mov_b64_e32 v[28:29], v[12:13]
	v_mov_b64_e32 v[26:27], v[10:11]
	v_mov_b64_e32 v[24:25], v[8:9]
	v_mov_b64_e32 v[22:23], v[6:7]
	v_mov_b64_e32 v[20:21], v[4:5]
	v_mov_b64_e32 v[18:19], v[2:3]
	v_mov_b64_e32 v[16:17], v[0:1]
	v_mov_b64_e32 v[44:45], v[12:13]
	v_mov_b64_e32 v[42:43], v[10:11]
	v_mov_b64_e32 v[40:41], v[8:9]
	v_mov_b64_e32 v[38:39], v[6:7]
	v_mov_b64_e32 v[36:37], v[4:5]
	v_mov_b64_e32 v[34:35], v[2:3]
	v_mov_b64_e32 v[32:33], v[0:1]
	v_mov_b64_e32 v[60:61], v[12:13]
	v_mov_b64_e32 v[58:59], v[10:11]
	v_mov_b64_e32 v[56:57], v[8:9]
	v_mov_b64_e32 v[54:55], v[6:7]
	v_mov_b64_e32 v[52:53], v[4:5]
	v_mov_b64_e32 v[50:51], v[2:3]
	v_mov_b64_e32 v[48:49], v[0:1]
	v_mov_b64_e32 v[76:77], v[12:13]
	v_mov_b64_e32 v[74:75], v[10:11]
	v_mov_b64_e32 v[72:73], v[8:9]
	v_mov_b64_e32 v[70:71], v[6:7]
	v_mov_b64_e32 v[68:69], v[4:5]
	v_mov_b64_e32 v[66:67], v[2:3]
	v_mov_b64_e32 v[64:65], v[0:1]
	v_mov_b64_e32 v[92:93], v[12:13]
	v_mov_b64_e32 v[90:91], v[10:11]
	v_mov_b64_e32 v[88:89], v[8:9]
	v_mov_b64_e32 v[86:87], v[6:7]
	v_mov_b64_e32 v[84:85], v[4:5]
	v_mov_b64_e32 v[82:83], v[2:3]
	v_mov_b64_e32 v[80:81], v[0:1]
	v_mov_b64_e32 v[108:109], v[12:13]
	v_mov_b64_e32 v[106:107], v[10:11]
	v_mov_b64_e32 v[104:105], v[8:9]
	v_mov_b64_e32 v[102:103], v[6:7]
	v_mov_b64_e32 v[100:101], v[4:5]
	v_mov_b64_e32 v[98:99], v[2:3]
	v_mov_b64_e32 v[96:97], v[0:1]
	v_mov_b64_e32 v[124:125], v[12:13]
	v_mov_b64_e32 v[122:123], v[10:11]
	v_mov_b64_e32 v[120:121], v[8:9]
	v_mov_b64_e32 v[118:119], v[6:7]
	v_mov_b64_e32 v[116:117], v[4:5]
	v_mov_b64_e32 v[114:115], v[2:3]
	v_mov_b64_e32 v[112:113], v[0:1]
	v_mov_b64_e32 v[140:141], v[12:13]
	v_mov_b64_e32 v[138:139], v[10:11]
	v_mov_b64_e32 v[136:137], v[8:9]
	v_mov_b64_e32 v[134:135], v[6:7]
	v_mov_b64_e32 v[132:133], v[4:5]
	v_mov_b64_e32 v[130:131], v[2:3]
	v_mov_b64_e32 v[128:129], v[0:1]
	s_waitcnt lgkmcnt(0)
	s_barrier
	s_branch .LBB0_714
	.p2align 8
